# FFN-up GEMM epilogue: the 16 masked 2-row HEAD/HALO stores per wave replaced by 2 full-wave stores packed with DPP row shifts (on top of in-projection epilogue widening)
# speedup vs baseline: 1.0036x; 1.0036x over previous
.LBB0_1098:
	ds_read_b128 v[130:133], v240
	ds_read_b128 v[134:137], v240 offset:1024
	ds_read_b128 v[138:141], v240 offset:2048
	ds_read_b128 v[142:145], v240 offset:3072
	s_add_u32 s50, s48, 0xfff80080
	s_addc_u32 s51, s49, -1
	s_cmp_eq_u32 s80, 28
	s_cselect_b32 s53, s41, s51
	s_cselect_b32 s52, s47, s50
	s_cselect_b32 s51, s39, s75
	s_cselect_b32 s50, s73, s74
	v_lshl_add_u64 v[168:169], s[48:49], 0, v[166:167]
	s_add_i32 m0, s21, 0xc000
	ds_read_b128 v[146:149], v241
	ds_read_b128 v[150:153], v241 offset:1024
	ds_read_b128 v[154:157], v241 offset:2048
	ds_read_b128 v[158:161], v241 offset:3072
	ds_read_b128 v[176:179], v241 offset:4096
	ds_read_b128 v[180:183], v241 offset:5120
	ds_read_b128 v[184:187], v241 offset:6144
	ds_read_b128 v[188:191], v241 offset:7168
	global_load_lds_dwordx4 v[168:169], off
	v_lshl_add_u64 v[168:169], s[48:49], 0, v[170:171]
	s_add_i32 m0, s21, 0xe000
	s_nop 0
	global_load_lds_dwordx4 v[168:169], off
	s_waitcnt lgkmcnt(8)
	s_barrier
	s_waitcnt lgkmcnt(0)
	s_setprio 1
	s_waitcnt lgkmcnt(0)
	v_mfma_f32_16x16x32_bf16 v[126:129], v[130:133], v[146:149], v[126:129]
	v_mfma_f32_16x16x32_bf16 v[122:125], v[138:141], v[146:149], v[122:125]
	v_mfma_f32_16x16x32_bf16 v[118:121], v[130:133], v[154:157], v[118:121]
	v_mfma_f32_16x16x32_bf16 v[114:117], v[138:141], v[154:157], v[114:117]
	v_mfma_f32_16x16x32_bf16 v[106:109], v[130:133], v[176:179], v[106:109]
	v_mfma_f32_16x16x32_bf16 v[98:101], v[138:141], v[176:179], v[98:101]
	v_mfma_f32_16x16x32_bf16 v[90:93], v[130:133], v[184:187], v[90:93]
	v_mfma_f32_16x16x32_bf16 v[82:85], v[138:141], v[184:187], v[82:85]
	v_mfma_f32_16x16x32_bf16 v[126:129], v[134:137], v[150:153], v[126:129]
	v_mfma_f32_16x16x32_bf16 v[122:125], v[142:145], v[150:153], v[122:125]
	v_mfma_f32_16x16x32_bf16 v[118:121], v[134:137], v[158:161], v[118:121]
	v_mfma_f32_16x16x32_bf16 v[114:117], v[142:145], v[158:161], v[114:117]
	v_mfma_f32_16x16x32_bf16 v[106:109], v[134:137], v[180:183], v[106:109]
	v_mfma_f32_16x16x32_bf16 v[98:101], v[142:145], v[180:183], v[98:101]
	v_mfma_f32_16x16x32_bf16 v[90:93], v[134:137], v[188:191], v[90:93]
	v_mfma_f32_16x16x32_bf16 v[82:85], v[142:145], v[188:191], v[82:85]
	s_setprio 0
	s_barrier
	s_add_i32 s81, s68, s56
	v_lshl_add_u64 v[168:169], s[50:51], 0, v[162:163]
	s_mov_b32 m0, s81
	ds_read_b128 v[192:195], v242
	ds_read_b128 v[196:199], v242 offset:1024
	ds_read_b128 v[200:203], v242 offset:2048
	ds_read_b128 v[204:207], v242 offset:3072
	global_load_lds_dwordx4 v[168:169], off
	v_lshl_add_u64 v[208:209], s[50:51], 0, v[164:165]
	s_add_i32 m0, s81, 0x2000
	s_nop 0
	global_load_lds_dwordx4 v[208:209], off
	s_barrier
	s_waitcnt lgkmcnt(0)
	s_setprio 1
	s_waitcnt lgkmcnt(0)
	v_mfma_f32_16x16x32_bf16 v[110:113], v[192:195], v[146:149], v[110:113]
	v_mfma_f32_16x16x32_bf16 v[102:105], v[200:203], v[146:149], v[102:105]
	v_mfma_f32_16x16x32_bf16 v[94:97], v[192:195], v[154:157], v[94:97]
	v_mfma_f32_16x16x32_bf16 v[86:89], v[200:203], v[154:157], v[86:89]
	v_mfma_f32_16x16x32_bf16 v[78:81], v[192:195], v[176:179], v[78:81]
	v_mfma_f32_16x16x32_bf16 v[74:77], v[200:203], v[176:179], v[74:77]
	v_mfma_f32_16x16x32_bf16 v[70:73], v[192:195], v[184:187], v[70:73]
	v_mfma_f32_16x16x32_bf16 v[66:69], v[200:203], v[184:187], v[66:69]
	v_mfma_f32_16x16x32_bf16 v[110:113], v[196:199], v[150:153], v[110:113]
	v_mfma_f32_16x16x32_bf16 v[102:105], v[204:207], v[150:153], v[102:105]
	v_mfma_f32_16x16x32_bf16 v[94:97], v[196:199], v[158:161], v[94:97]
	v_mfma_f32_16x16x32_bf16 v[86:89], v[204:207], v[158:161], v[86:89]
	v_mfma_f32_16x16x32_bf16 v[78:81], v[196:199], v[180:183], v[78:81]
	v_mfma_f32_16x16x32_bf16 v[74:77], v[204:207], v[180:183], v[74:77]
	v_mfma_f32_16x16x32_bf16 v[70:73], v[196:199], v[188:191], v[70:73]
	v_mfma_f32_16x16x32_bf16 v[66:69], v[204:207], v[188:191], v[66:69]
	s_setprio 0
	s_mov_b32 m0, s21
	v_lshl_add_u64 v[210:211], s[52:53], 0, v[162:163]
	s_barrier
	ds_read_b128 v[146:149], v241 offset:16384
	ds_read_b128 v[150:153], v241 offset:17408
	ds_read_b128 v[154:157], v241 offset:18432
	ds_read_b128 v[158:161], v241 offset:19456
	ds_read_b128 v[176:179], v241 offset:20480
	ds_read_b128 v[180:183], v241 offset:21504
	ds_read_b128 v[184:187], v241 offset:22528
	ds_read_b128 v[188:191], v241 offset:23552
	global_load_lds_dwordx4 v[210:211], off
	v_lshl_add_u64 v[212:213], s[52:53], 0, v[164:165]
	s_mov_b32 m0, s59
	s_nop 0
	global_load_lds_dwordx4 v[212:213], off
	s_barrier
	s_waitcnt lgkmcnt(0)
	s_setprio 1
	s_waitcnt lgkmcnt(0)
	v_mfma_f32_16x16x32_bf16 v[62:65], v[130:133], v[146:149], v[62:65]
	v_mfma_f32_16x16x32_bf16 v[58:61], v[138:141], v[146:149], v[58:61]
	v_mfma_f32_16x16x32_bf16 v[54:57], v[130:133], v[154:157], v[54:57]
	v_mfma_f32_16x16x32_bf16 v[50:53], v[138:141], v[154:157], v[50:53]
	v_mfma_f32_16x16x32_bf16 v[42:45], v[130:133], v[176:179], v[42:45]
	v_mfma_f32_16x16x32_bf16 v[34:37], v[138:141], v[176:179], v[34:37]
	v_mfma_f32_16x16x32_bf16 v[26:29], v[130:133], v[184:187], v[26:29]
	v_mfma_f32_16x16x32_bf16 v[18:21], v[138:141], v[184:187], v[18:21]
	v_mfma_f32_16x16x32_bf16 v[62:65], v[134:137], v[150:153], v[62:65]
	v_mfma_f32_16x16x32_bf16 v[58:61], v[142:145], v[150:153], v[58:61]
	v_mfma_f32_16x16x32_bf16 v[54:57], v[134:137], v[158:161], v[54:57]
	v_mfma_f32_16x16x32_bf16 v[50:53], v[142:145], v[158:161], v[50:53]
	v_mfma_f32_16x16x32_bf16 v[42:45], v[134:137], v[180:183], v[42:45]
	v_mfma_f32_16x16x32_bf16 v[34:37], v[142:145], v[180:183], v[34:37]
	v_mfma_f32_16x16x32_bf16 v[26:29], v[134:137], v[188:191], v[26:29]
	v_mfma_f32_16x16x32_bf16 v[18:21], v[142:145], v[188:191], v[18:21]
	s_setprio 0
	s_barrier
	s_add_u32 s82, s50, 0x80000
	s_addc_u32 s83, s51, 0
	s_add_i32 s81, s69, s56
	v_lshl_add_u64 v[130:131], s[82:83], 0, v[162:163]
	s_mov_b32 m0, s81
	s_nop 0
	global_load_lds_dwordx4 v[130:131], off
	v_lshl_add_u64 v[130:131], s[82:83], 0, v[164:165]
	s_add_i32 m0, s81, 0x2000
	s_nop 0
	global_load_lds_dwordx4 v[130:131], off
	s_waitcnt vmcnt(6)
	s_barrier
	s_setprio 1
	v_mfma_f32_16x16x32_bf16 v[46:49], v[192:195], v[146:149], v[46:49]
	v_mfma_f32_16x16x32_bf16 v[38:41], v[200:203], v[146:149], v[38:41]
	v_mfma_f32_16x16x32_bf16 v[30:33], v[192:195], v[154:157], v[30:33]
	v_mfma_f32_16x16x32_bf16 v[22:25], v[200:203], v[154:157], v[22:25]
	v_mfma_f32_16x16x32_bf16 v[14:17], v[192:195], v[176:179], v[14:17]
	v_mfma_f32_16x16x32_bf16 v[10:13], v[200:203], v[176:179], v[10:13]
	v_mfma_f32_16x16x32_bf16 v[6:9], v[192:195], v[184:187], v[6:9]
	v_mfma_f32_16x16x32_bf16 v[2:5], v[200:203], v[184:187], v[2:5]
	v_mfma_f32_16x16x32_bf16 v[46:49], v[196:199], v[150:153], v[46:49]
	v_mfma_f32_16x16x32_bf16 v[38:41], v[204:207], v[150:153], v[38:41]
	v_mfma_f32_16x16x32_bf16 v[30:33], v[196:199], v[158:161], v[30:33]
	v_mfma_f32_16x16x32_bf16 v[22:25], v[204:207], v[158:161], v[22:25]
	v_mfma_f32_16x16x32_bf16 v[14:17], v[196:199], v[180:183], v[14:17]
	v_mfma_f32_16x16x32_bf16 v[10:13], v[204:207], v[180:183], v[10:13]
	v_mfma_f32_16x16x32_bf16 v[6:9], v[196:199], v[188:191], v[6:9]
	v_mfma_f32_16x16x32_bf16 v[2:5], v[204:207], v[188:191], v[2:5]
	s_setprio 0
	s_add_i32 s81, 0, 0x18000
	v_add_u32_e32 v142, s81, v236
	s_barrier
	ds_read_b128 v[130:133], v142
	ds_read_b128 v[134:137], v142 offset:1024
	ds_read_b128 v[138:141], v142 offset:2048
	ds_read_b128 v[142:145], v142 offset:3072
	s_add_u32 s52, s52, 0x80000
	s_addc_u32 s53, s53, 0
	s_mov_b32 m0, s60
	v_lshl_add_u64 v[192:193], s[52:53], 0, v[162:163]
	ds_read_b128 v[146:149], v241 offset:32768
	ds_read_b128 v[150:153], v241 offset:33792
	ds_read_b128 v[154:157], v241 offset:34816
	ds_read_b128 v[158:161], v241 offset:35840
	ds_read_b128 v[176:179], v241 offset:36864
	ds_read_b128 v[180:183], v241 offset:37888
	ds_read_b128 v[184:187], v241 offset:38912
	ds_read_b128 v[188:191], v241 offset:39936
	global_load_lds_dwordx4 v[192:193], off
	v_lshl_add_u64 v[192:193], s[52:53], 0, v[164:165]
	s_mov_b32 m0, s61
	s_nop 0
	global_load_lds_dwordx4 v[192:193], off
	s_waitcnt lgkmcnt(8)
	s_barrier
	s_waitcnt lgkmcnt(0)
	s_setprio 1
	s_waitcnt lgkmcnt(0)
	v_mfma_f32_16x16x32_bf16 v[126:129], v[130:133], v[146:149], v[126:129]
	v_mfma_f32_16x16x32_bf16 v[122:125], v[138:141], v[146:149], v[122:125]
	v_mfma_f32_16x16x32_bf16 v[118:121], v[130:133], v[154:157], v[118:121]
	v_mfma_f32_16x16x32_bf16 v[114:117], v[138:141], v[154:157], v[114:117]
	v_mfma_f32_16x16x32_bf16 v[106:109], v[130:133], v[176:179], v[106:109]
	v_mfma_f32_16x16x32_bf16 v[98:101], v[138:141], v[176:179], v[98:101]
	v_mfma_f32_16x16x32_bf16 v[90:93], v[130:133], v[184:187], v[90:93]
	v_mfma_f32_16x16x32_bf16 v[82:85], v[138:141], v[184:187], v[82:85]
	v_mfma_f32_16x16x32_bf16 v[126:129], v[134:137], v[150:153], v[126:129]
	v_mfma_f32_16x16x32_bf16 v[122:125], v[142:145], v[150:153], v[122:125]
	v_mfma_f32_16x16x32_bf16 v[118:121], v[134:137], v[158:161], v[118:121]
	v_mfma_f32_16x16x32_bf16 v[114:117], v[142:145], v[158:161], v[114:117]
	v_mfma_f32_16x16x32_bf16 v[106:109], v[134:137], v[180:183], v[106:109]
	v_mfma_f32_16x16x32_bf16 v[98:101], v[142:145], v[180:183], v[98:101]
	v_mfma_f32_16x16x32_bf16 v[90:93], v[134:137], v[188:191], v[90:93]
	v_mfma_f32_16x16x32_bf16 v[82:85], v[142:145], v[188:191], v[82:85]
	s_setprio 0
	s_barrier
	s_add_i32 s52, 0, 0x1c000
	s_add_i32 s53, s81, s56
	v_add_u32_e32 v204, s52, v236
	v_lshl_add_u64 v[168:169], v[168:169], 0, s[36:37]
	s_mov_b32 m0, s53
	ds_read_b128 v[192:195], v204
	ds_read_b128 v[196:199], v204 offset:1024
	ds_read_b128 v[200:203], v204 offset:2048
	ds_read_b128 v[204:207], v204 offset:3072
	global_load_lds_dwordx4 v[168:169], off
	v_lshl_add_u64 v[168:169], v[208:209], 0, s[36:37]
	s_add_i32 m0, s53, 0x2000
	s_nop 0
	global_load_lds_dwordx4 v[168:169], off
	s_barrier
	s_waitcnt lgkmcnt(0)
	s_setprio 1
	s_waitcnt lgkmcnt(0)
	v_mfma_f32_16x16x32_bf16 v[110:113], v[192:195], v[146:149], v[110:113]
	v_mfma_f32_16x16x32_bf16 v[102:105], v[200:203], v[146:149], v[102:105]
	v_mfma_f32_16x16x32_bf16 v[94:97], v[192:195], v[154:157], v[94:97]
	v_mfma_f32_16x16x32_bf16 v[86:89], v[200:203], v[154:157], v[86:89]
	v_mfma_f32_16x16x32_bf16 v[78:81], v[192:195], v[176:179], v[78:81]
	v_mfma_f32_16x16x32_bf16 v[74:77], v[200:203], v[176:179], v[74:77]
	v_mfma_f32_16x16x32_bf16 v[70:73], v[192:195], v[184:187], v[70:73]
	v_mfma_f32_16x16x32_bf16 v[66:69], v[200:203], v[184:187], v[66:69]
	v_mfma_f32_16x16x32_bf16 v[110:113], v[196:199], v[150:153], v[110:113]
	v_mfma_f32_16x16x32_bf16 v[102:105], v[204:207], v[150:153], v[102:105]
	v_mfma_f32_16x16x32_bf16 v[94:97], v[196:199], v[158:161], v[94:97]
	v_mfma_f32_16x16x32_bf16 v[86:89], v[204:207], v[158:161], v[86:89]
	v_mfma_f32_16x16x32_bf16 v[78:81], v[196:199], v[180:183], v[78:81]
	v_mfma_f32_16x16x32_bf16 v[74:77], v[204:207], v[180:183], v[74:77]
	v_mfma_f32_16x16x32_bf16 v[70:73], v[196:199], v[188:191], v[70:73]
	v_mfma_f32_16x16x32_bf16 v[66:69], v[204:207], v[188:191], v[66:69]
	s_setprio 0
	s_mov_b32 m0, s64
	v_lshl_add_u64 v[168:169], v[210:211], 0, s[36:37]
	s_barrier
	ds_read_b128 v[146:149], v241 offset:49152
	ds_read_b128 v[150:153], v241 offset:50176
	ds_read_b128 v[154:157], v241 offset:51200
	ds_read_b128 v[158:161], v241 offset:52224
	ds_read_b128 v[176:179], v241 offset:53248
	ds_read_b128 v[180:183], v241 offset:54272
	ds_read_b128 v[184:187], v241 offset:55296
	ds_read_b128 v[188:191], v241 offset:56320
	global_load_lds_dwordx4 v[168:169], off
	v_lshl_add_u64 v[168:169], v[212:213], 0, s[36:37]
	s_mov_b32 m0, s65
	s_nop 0
	global_load_lds_dwordx4 v[168:169], off
	s_barrier
	s_waitcnt lgkmcnt(0)
	s_setprio 1
	s_waitcnt lgkmcnt(0)
	v_mfma_f32_16x16x32_bf16 v[62:65], v[130:133], v[146:149], v[62:65]
	v_mfma_f32_16x16x32_bf16 v[58:61], v[138:141], v[146:149], v[58:61]
	v_mfma_f32_16x16x32_bf16 v[54:57], v[130:133], v[154:157], v[54:57]
	v_mfma_f32_16x16x32_bf16 v[50:53], v[138:141], v[154:157], v[50:53]
	v_mfma_f32_16x16x32_bf16 v[42:45], v[130:133], v[176:179], v[42:45]
	v_mfma_f32_16x16x32_bf16 v[34:37], v[138:141], v[176:179], v[34:37]
	v_mfma_f32_16x16x32_bf16 v[26:29], v[130:133], v[184:187], v[26:29]
	v_mfma_f32_16x16x32_bf16 v[18:21], v[138:141], v[184:187], v[18:21]
	v_mfma_f32_16x16x32_bf16 v[62:65], v[134:137], v[150:153], v[62:65]
	v_mfma_f32_16x16x32_bf16 v[58:61], v[142:145], v[150:153], v[58:61]
	v_mfma_f32_16x16x32_bf16 v[54:57], v[134:137], v[158:161], v[54:57]
	v_mfma_f32_16x16x32_bf16 v[50:53], v[142:145], v[158:161], v[50:53]
	v_mfma_f32_16x16x32_bf16 v[42:45], v[134:137], v[180:183], v[42:45]
	v_mfma_f32_16x16x32_bf16 v[34:37], v[142:145], v[180:183], v[34:37]
	v_mfma_f32_16x16x32_bf16 v[26:29], v[134:137], v[188:191], v[26:29]
	v_mfma_f32_16x16x32_bf16 v[18:21], v[142:145], v[188:191], v[18:21]
	s_setprio 0
	s_barrier
	s_add_u32 s50, s50, 0x80080
	s_addc_u32 s51, s51, 0
	s_add_i32 s52, s52, s56
	v_lshl_add_u64 v[130:131], s[50:51], 0, v[162:163]
	s_mov_b32 m0, s52
	s_nop 0
	global_load_lds_dwordx4 v[130:131], off
	v_lshl_add_u64 v[130:131], s[50:51], 0, v[164:165]
	s_add_i32 m0, s52, 0x2000
	s_nop 0
	global_load_lds_dwordx4 v[130:131], off
	s_waitcnt vmcnt(6)
	s_barrier
	s_setprio 1
	v_mfma_f32_16x16x32_bf16 v[46:49], v[192:195], v[146:149], v[46:49]
	v_mfma_f32_16x16x32_bf16 v[38:41], v[200:203], v[146:149], v[38:41]
	v_mfma_f32_16x16x32_bf16 v[30:33], v[192:195], v[154:157], v[30:33]
	v_mfma_f32_16x16x32_bf16 v[22:25], v[200:203], v[154:157], v[22:25]
	v_mfma_f32_16x16x32_bf16 v[14:17], v[192:195], v[176:179], v[14:17]
	v_mfma_f32_16x16x32_bf16 v[10:13], v[200:203], v[176:179], v[10:13]
	v_mfma_f32_16x16x32_bf16 v[6:9], v[192:195], v[184:187], v[6:9]
	v_mfma_f32_16x16x32_bf16 v[2:5], v[200:203], v[184:187], v[2:5]
	v_mfma_f32_16x16x32_bf16 v[46:49], v[196:199], v[150:153], v[46:49]
	v_mfma_f32_16x16x32_bf16 v[38:41], v[204:207], v[150:153], v[38:41]
	v_mfma_f32_16x16x32_bf16 v[30:33], v[196:199], v[158:161], v[30:33]
	v_mfma_f32_16x16x32_bf16 v[22:25], v[204:207], v[158:161], v[22:25]
	v_mfma_f32_16x16x32_bf16 v[14:17], v[196:199], v[180:183], v[14:17]
	v_mfma_f32_16x16x32_bf16 v[10:13], v[204:207], v[180:183], v[10:13]
	v_mfma_f32_16x16x32_bf16 v[6:9], v[196:199], v[188:191], v[6:9]
	v_mfma_f32_16x16x32_bf16 v[2:5], v[204:207], v[188:191], v[2:5]
	s_setprio 0
	s_add_i32 s80, s80, 2
	s_add_u32 s48, s48, 0x100
	s_addc_u32 s49, s49, 0
	s_add_u32 s74, s74, 0x100
	s_addc_u32 s75, s75, 0
	s_cmp_gt_u32 s80, 29
	s_barrier
	s_cbranch_scc0 .LBB0_1098
	v_lshl_or_b32 v176, s46, 7, v239
	s_cmp_gt_i32 s20, 63
	v_ashrrev_i32_e32 v177, 31, v176
	s_mov_b64 s[46:47], -1
	s_cbranch_scc1 .LBB0_1141
	v_lshlrev_b64 v[130:131], 2, v[176:177]
	v_lshl_add_u64 v[186:187], s[12:13], 0, v[130:131]
	v_add_co_u32_e32 v146, vcc, 0x5000, v186
	v_lshl_add_u64 v[184:185], s[30:31], 0, v[130:131]
	s_nop 0
	v_addc_co_u32_e32 v147, vcc, 0, v187, vcc
	v_add_co_u32_e32 v150, vcc, 0x5000, v184
	v_lshl_add_u64 v[182:183], s[34:35], 0, v[130:131]
	v_lshl_add_u64 v[180:181], s[14:15], 0, v[130:131]
	v_addc_co_u32_e32 v151, vcc, 0, v185, vcc
	global_load_dwordx4 v[134:137], v[186:187], off
	global_load_dwordx4 v[142:145], v[184:185], off
	global_load_dwordx4 v[138:141], v[182:183], off
	global_load_dwordx4 v[130:133], v[180:181], off
	s_nop 0
	global_load_dwordx4 v[146:149], v[146:147], off offset:2048
	s_nop 0
	global_load_dwordx4 v[154:157], v[150:151], off offset:2048
	v_add_co_u32_e32 v150, vcc, 0x5000, v182
	s_lshl_b32 s39, s20, 2
	s_nop 0
	v_addc_co_u32_e32 v151, vcc, 0, v183, vcc
	global_load_dwordx4 v[158:161], v[150:151], off offset:2048
	v_add_co_u32_e32 v150, vcc, 0x5000, v180
	s_add_i32 s39, s39, s55
	s_nop 0
	v_addc_co_u32_e32 v151, vcc, 0, v181, vcc
	global_load_dwordx4 v[150:153], v[150:151], off offset:2048
	s_lshl_b32 s41, s39, 1
	v_add_u32_e32 v168, s41, v1
	v_mad_i64_i32 v[168:169], s[46:47], v168, s71, 0
	v_lshl_add_u64 v[168:169], s[24:25], 0, v[168:169]
	v_mov_b32_dpp v206, v126 row_shr:1 row_mask:0xf bank_mask:0xf bound_ctrl:1
	v_mov_b32_dpp v188, v126 row_shr:2 row_mask:0xf bank_mask:0xf bound_ctrl:1
	v_mov_b32_dpp v200, v126 row_shl:15 row_mask:0xf bank_mask:0xf bound_ctrl:1
	v_mov_b32_dpp v198, v126 row_shl:14 row_mask:0xf bank_mask:0xf bound_ctrl:1
	v_mov_b32_dpp v207, v127 row_shr:1 row_mask:0xf bank_mask:0xf bound_ctrl:1
	v_mov_b32_dpp v189, v127 row_shr:2 row_mask:0xf bank_mask:0xf bound_ctrl:1
	v_mov_b32_dpp v201, v127 row_shl:15 row_mask:0xf bank_mask:0xf bound_ctrl:1
	v_mov_b32_dpp v199, v127 row_shl:14 row_mask:0xf bank_mask:0xf bound_ctrl:1
	v_mov_b32_dpp v210, v128 row_shr:1 row_mask:0xf bank_mask:0xf bound_ctrl:1
	v_mov_b32_dpp v208, v128 row_shr:2 row_mask:0xf bank_mask:0xf bound_ctrl:1
	v_mov_b32_dpp v204, v128 row_shl:15 row_mask:0xf bank_mask:0xf bound_ctrl:1
	v_mov_b32_dpp v202, v128 row_shl:14 row_mask:0xf bank_mask:0xf bound_ctrl:1
	v_mov_b32_dpp v211, v129 row_shr:1 row_mask:0xf bank_mask:0xf bound_ctrl:1
	v_mov_b32_dpp v209, v129 row_shr:2 row_mask:0xf bank_mask:0xf bound_ctrl:1
	v_mov_b32_dpp v205, v129 row_shl:15 row_mask:0xf bank_mask:0xf bound_ctrl:1
	v_mov_b32_dpp v203, v129 row_shl:14 row_mask:0xf bank_mask:0xf bound_ctrl:1
	v_lshl_add_u64 v[178:179], v[176:177], 2, v[168:169]
	s_and_saveexec_b64 s[46:47], s[4:5]
	s_cbranch_execz .LBB0_1102
.LBB0_1102:
	s_or_b64 exec, exec, s[46:47]
	v_mov_b32_dpp v214, v110 row_shr:1 row_mask:0xf bank_mask:0xf bound_ctrl:1
	v_mov_b32_dpp v212, v110 row_shr:2 row_mask:0xf bank_mask:0xf bound_ctrl:1
	v_mov_b32_dpp v192, v110 row_shl:15 row_mask:0xf bank_mask:0xf bound_ctrl:1
	v_mov_b32_dpp v190, v110 row_shl:14 row_mask:0xf bank_mask:0xf bound_ctrl:1
	v_mov_b32_dpp v215, v111 row_shr:1 row_mask:0xf bank_mask:0xf bound_ctrl:1
	v_mov_b32_dpp v213, v111 row_shr:2 row_mask:0xf bank_mask:0xf bound_ctrl:1
	v_mov_b32_dpp v193, v111 row_shl:15 row_mask:0xf bank_mask:0xf bound_ctrl:1
	v_mov_b32_dpp v191, v111 row_shl:14 row_mask:0xf bank_mask:0xf bound_ctrl:1
	v_mov_b32_dpp v218, v112 row_shr:1 row_mask:0xf bank_mask:0xf bound_ctrl:1
	v_mov_b32_dpp v216, v112 row_shr:2 row_mask:0xf bank_mask:0xf bound_ctrl:1
	v_mov_b32_dpp v196, v112 row_shl:15 row_mask:0xf bank_mask:0xf bound_ctrl:1
	v_mov_b32_dpp v194, v112 row_shl:14 row_mask:0xf bank_mask:0xf bound_ctrl:1
	v_mov_b32_dpp v219, v113 row_shr:1 row_mask:0xf bank_mask:0xf bound_ctrl:1
	v_mov_b32_dpp v217, v113 row_shr:2 row_mask:0xf bank_mask:0xf bound_ctrl:1
	v_mov_b32_dpp v197, v113 row_shl:15 row_mask:0xf bank_mask:0xf bound_ctrl:1
	v_mov_b32_dpp v195, v113 row_shl:14 row_mask:0xf bank_mask:0xf bound_ctrl:1
	s_and_saveexec_b64 s[46:47], s[4:5]
	s_cbranch_execz .LBB0_1104
	v_add_co_u32_e32 v168, vcc, 0x5000, v178
	s_nop 1
	v_addc_co_u32_e32 v169, vcc, 0, v179, vcc
.LBB0_1104:
	s_or_b64 exec, exec, s[46:47]
	v_lshl_or_b32 v243, s39, 6, v1
	s_and_saveexec_b64 s[46:47], s[8:9]
	s_cbranch_execz .LBB0_1106
	v_pk_add_f32 v[206:207], v[206:207], 0 op_sel_hi:[1,0]
	v_pk_add_f32 v[210:211], v[210:211], 0 op_sel_hi:[1,0]
	s_waitcnt vmcnt(0)
	v_pk_mul_f32 v[206:207], v[142:143], v[206:207]
	v_pk_add_f32 v[188:189], v[188:189], 0 op_sel_hi:[1,0]
	v_pk_mul_f32 v[210:211], v[144:145], v[210:211]
	v_pk_fma_f32 v[206:207], v[126:127], v[138:139], v[206:207]
	v_pk_add_f32 v[208:209], v[208:209], 0 op_sel_hi:[1,0]
	v_pk_fma_f32 v[210:211], v[128:129], v[140:141], v[210:211]
	v_pk_fma_f32 v[188:189], v[134:135], v[188:189], v[206:207]
	v_pk_fma_f32 v[206:207], v[136:137], v[208:209], v[210:211]
	v_pk_add_f32 v[188:189], v[130:131], v[188:189]
	v_pk_add_f32 v[206:207], v[132:133], v[206:207]
	v_mul_f32_e32 v208, 0xbfb8aa3b, v188
	v_mul_f32_e32 v209, 0xbfb8aa3b, v189
	v_exp_f32_e32 v208, v208
	v_exp_f32_e32 v209, v209
	v_mul_f32_e32 v210, 0xbfb8aa3b, v206
	v_mul_f32_e32 v211, 0xbfb8aa3b, v207
	v_exp_f32_e32 v210, v210
	v_exp_f32_e32 v211, v211
	v_add_f32_e32 v208, 1.0, v208
	v_add_f32_e32 v209, 1.0, v209
	v_pk_add_f32 v[168:169], v[214:215], 0 op_sel_hi:[1,0]
	v_rcp_f32_e32 v208, v208
	v_rcp_f32_e32 v209, v209
	v_add_f32_e32 v210, 1.0, v210
	v_add_f32_e32 v211, 1.0, v211
	v_pk_add_f32 v[214:215], v[218:219], 0 op_sel_hi:[1,0]
	v_pk_mul_f32 v[168:169], v[154:155], v[168:169]
	v_rcp_f32_e32 v210, v210
	v_rcp_f32_e32 v211, v211
	v_pk_add_f32 v[212:213], v[212:213], 0 op_sel_hi:[1,0]
	v_pk_mul_f32 v[214:215], v[156:157], v[214:215]
	v_pk_fma_f32 v[168:169], v[110:111], v[158:159], v[168:169]
	v_pk_add_f32 v[216:217], v[216:217], 0 op_sel_hi:[1,0]
	v_pk_fma_f32 v[214:215], v[112:113], v[160:161], v[214:215]
	v_pk_fma_f32 v[168:169], v[146:147], v[212:213], v[168:169]
	v_pk_fma_f32 v[212:213], v[148:149], v[216:217], v[214:215]
	v_pk_add_f32 v[168:169], v[150:151], v[168:169]
	v_pk_mul_f32 v[188:189], v[188:189], v[208:209]
	v_pk_add_f32 v[212:213], v[152:153], v[212:213]
	v_pk_mul_f32 v[168:169], v[188:189], v[168:169]
	v_pk_mul_f32 v[188:189], v[206:207], v[210:211]
	v_cvt_pk_bf16_f32 v168, v168, v169
	v_pk_mul_f32 v[188:189], v[188:189], v[212:213]
	s_nop 0
	v_cvt_pk_bf16_f32 v169, v188, v189
	v_mov_b64_e32 v[188:189], s[22:23]
	v_mad_i64_i32 v[188:189], s[48:49], v243, s72, v[188:189]
	v_lshl_add_u64 v[188:189], v[176:177], 1, v[188:189]
	global_store_dwordx2 v[188:189], v[168:169], off
.LBB0_1106:
	s_or_b64 exec, exec, s[46:47]
	v_add_u32_e32 v168, s41, v237
	v_mad_i64_i32 v[188:189], s[46:47], v168, s71, 0
	s_nop 0
	v_mov_b32_dpp v168, v118 row_shr:1 row_mask:0xf bank_mask:0xf bound_ctrl:1
	v_mov_b32_dpp v169, v119 row_shr:1 row_mask:0xf bank_mask:0xf bound_ctrl:1
	v_mov_b32_dpp v212, v120 row_shr:1 row_mask:0xf bank_mask:0xf bound_ctrl:1
	v_mov_b32_dpp v213, v121 row_shr:1 row_mask:0xf bank_mask:0xf bound_ctrl:1
	v_mov_b32_dpp v214, v120 row_shr:2 row_mask:0xf bank_mask:0xf bound_ctrl:1
	v_pk_add_f32 v[204:205], v[204:205], v[212:213]
	v_pk_add_f32 v[168:169], v[200:201], v[168:169]
	v_mov_b32_dpp v215, v121 row_shr:2 row_mask:0xf bank_mask:0xf bound_ctrl:1
	v_mov_b32_dpp v206, v118 row_shr:2 row_mask:0xf bank_mask:0xf bound_ctrl:1
	v_mov_b32_dpp v207, v119 row_shr:2 row_mask:0xf bank_mask:0xf bound_ctrl:1
	v_pk_add_f32 v[200:201], v[202:203], v[214:215]
	s_waitcnt vmcnt(0)
	v_pk_mul_f32 v[168:169], v[142:143], v[168:169]
	v_pk_mul_f32 v[202:203], v[144:145], v[204:205]
	v_pk_add_f32 v[198:199], v[198:199], v[206:207]
	v_pk_fma_f32 v[202:203], v[120:121], v[140:141], v[202:203]
	v_pk_fma_f32 v[168:169], v[118:119], v[138:139], v[168:169]
	v_mov_b32_dpp v204, v96 row_shr:1 row_mask:0xf bank_mask:0xf bound_ctrl:1
	v_pk_fma_f32 v[168:169], v[134:135], v[198:199], v[168:169]
	v_pk_fma_f32 v[198:199], v[136:137], v[200:201], v[202:203]
	v_mov_b32_dpp v200, v94 row_shr:1 row_mask:0xf bank_mask:0xf bound_ctrl:1
	v_mov_b32_dpp v201, v95 row_shr:1 row_mask:0xf bank_mask:0xf bound_ctrl:1
	v_mov_b32_dpp v205, v97 row_shr:1 row_mask:0xf bank_mask:0xf bound_ctrl:1
	v_pk_add_f32 v[196:197], v[196:197], v[204:205]
	v_pk_add_f32 v[192:193], v[192:193], v[200:201]
	v_mov_b32_dpp v202, v94 row_shr:2 row_mask:0xf bank_mask:0xf bound_ctrl:1
	v_mov_b32_dpp v203, v95 row_shr:2 row_mask:0xf bank_mask:0xf bound_ctrl:1
	v_mov_b32_dpp v206, v96 row_shr:2 row_mask:0xf bank_mask:0xf bound_ctrl:1
	v_mov_b32_dpp v207, v97 row_shr:2 row_mask:0xf bank_mask:0xf bound_ctrl:1
	v_pk_mul_f32 v[192:193], v[154:155], v[192:193]
	v_pk_mul_f32 v[196:197], v[156:157], v[196:197]
	v_pk_add_f32 v[168:169], v[130:131], v[168:169]
	v_pk_add_f32 v[194:195], v[194:195], v[206:207]
	v_pk_add_f32 v[190:191], v[190:191], v[202:203]
	v_pk_fma_f32 v[196:197], v[96:97], v[160:161], v[196:197]
	v_pk_fma_f32 v[192:193], v[94:95], v[158:159], v[192:193]
	v_pk_add_f32 v[198:199], v[132:133], v[198:199]
	v_pk_fma_f32 v[190:191], v[146:147], v[190:191], v[192:193]
	v_pk_fma_f32 v[192:193], v[148:149], v[194:195], v[196:197]
	v_mul_f32_e32 v194, 0xbfb8aa3b, v168
	v_mul_f32_e32 v195, 0xbfb8aa3b, v169
	v_exp_f32_e32 v194, v194
	v_exp_f32_e32 v195, v195
	v_mul_f32_e32 v196, 0xbfb8aa3b, v198
	v_mul_f32_e32 v197, 0xbfb8aa3b, v199
	v_exp_f32_e32 v196, v196
	v_exp_f32_e32 v197, v197
	v_add_f32_e32 v194, 1.0, v194
	v_add_f32_e32 v195, 1.0, v195
	v_rcp_f32_e32 v194, v194
	v_rcp_f32_e32 v195, v195
	v_add_f32_e32 v196, 1.0, v196
	v_add_f32_e32 v197, 1.0, v197
	v_rcp_f32_e32 v196, v196
	v_rcp_f32_e32 v197, v197
	v_pk_add_f32 v[190:191], v[150:151], v[190:191]
	v_pk_mul_f32 v[168:169], v[168:169], v[194:195]
	v_pk_add_f32 v[192:193], v[152:153], v[192:193]
	v_pk_mul_f32 v[168:169], v[168:169], v[190:191]
	v_pk_mul_f32 v[190:191], v[198:199], v[196:197]
	v_cvt_pk_bf16_f32 v168, v168, v169
	v_pk_mul_f32 v[190:191], v[190:191], v[192:193]
	v_mov_b64_e32 v[194:195], s[22:23]
	v_cvt_pk_bf16_f32 v169, v190, v191
	v_or_b32_e32 v190, 16, v243
	v_mad_i64_i32 v[190:191], s[46:47], v190, s72, v[194:195]
	v_lshlrev_b64 v[196:197], 1, v[176:177]
	v_lshl_add_u64 v[192:193], v[190:191], 0, v[196:197]
	v_mov_b32_dpp v208, v118 row_shl:15 row_mask:0xf bank_mask:0xf bound_ctrl:1
	v_mov_b32_dpp v209, v119 row_shl:15 row_mask:0xf bank_mask:0xf bound_ctrl:1
	global_store_dwordx2 v[192:193], v[168:169], off
	v_mov_b32_dpp v168, v106 row_shr:1 row_mask:0xf bank_mask:0xf bound_ctrl:1
	v_mov_b32_dpp v169, v107 row_shr:1 row_mask:0xf bank_mask:0xf bound_ctrl:1
	v_mov_b32_dpp v216, v120 row_shl:15 row_mask:0xf bank_mask:0xf bound_ctrl:1
	v_mov_b32_dpp v218, v120 row_shl:14 row_mask:0xf bank_mask:0xf bound_ctrl:1
	v_mov_b32_dpp v217, v121 row_shl:15 row_mask:0xf bank_mask:0xf bound_ctrl:1
	v_mov_b32_dpp v219, v121 row_shl:14 row_mask:0xf bank_mask:0xf bound_ctrl:1
	v_mov_b32_dpp v206, v108 row_shr:1 row_mask:0xf bank_mask:0xf bound_ctrl:1
	v_mov_b32_dpp v224, v108 row_shr:2 row_mask:0xf bank_mask:0xf bound_ctrl:1
	v_mov_b32_dpp v207, v109 row_shr:1 row_mask:0xf bank_mask:0xf bound_ctrl:1
	v_pk_add_f32 v[168:169], v[208:209], v[168:169]
	v_mov_b32_dpp v225, v109 row_shr:2 row_mask:0xf bank_mask:0xf bound_ctrl:1
	v_mov_b32_dpp v210, v118 row_shl:14 row_mask:0xf bank_mask:0xf bound_ctrl:1
	v_mov_b32_dpp v211, v119 row_shl:14 row_mask:0xf bank_mask:0xf bound_ctrl:1
	v_mov_b32_dpp v212, v94 row_shl:15 row_mask:0xf bank_mask:0xf bound_ctrl:1
	v_mov_b32_dpp v213, v95 row_shl:15 row_mask:0xf bank_mask:0xf bound_ctrl:1
	v_mov_b32_dpp v220, v96 row_shl:15 row_mask:0xf bank_mask:0xf bound_ctrl:1
	v_mov_b32_dpp v221, v97 row_shl:15 row_mask:0xf bank_mask:0xf bound_ctrl:1
	v_mov_b32_dpp v204, v106 row_shr:2 row_mask:0xf bank_mask:0xf bound_ctrl:1
	v_mov_b32_dpp v205, v107 row_shr:2 row_mask:0xf bank_mask:0xf bound_ctrl:1
	v_pk_add_f32 v[206:207], v[216:217], v[206:207]
	v_pk_add_f32 v[208:209], v[218:219], v[224:225]
	v_pk_mul_f32 v[168:169], v[142:143], v[168:169]
	v_mov_b32_dpp v218, v78 row_shr:1 row_mask:0xf bank_mask:0xf bound_ctrl:1
	v_mov_b32_dpp v219, v79 row_shr:1 row_mask:0xf bank_mask:0xf bound_ctrl:1
	v_mov_b32_dpp v226, v80 row_shr:1 row_mask:0xf bank_mask:0xf bound_ctrl:1
	v_mov_b32_dpp v227, v81 row_shr:1 row_mask:0xf bank_mask:0xf bound_ctrl:1
	v_pk_add_f32 v[204:205], v[210:211], v[204:205]
	v_pk_mul_f32 v[206:207], v[144:145], v[206:207]
	v_pk_fma_f32 v[168:169], v[106:107], v[138:139], v[168:169]
	v_pk_add_f32 v[220:221], v[220:221], v[226:227]
	v_pk_add_f32 v[212:213], v[212:213], v[218:219]
	v_mov_b32_dpp v214, v94 row_shl:14 row_mask:0xf bank_mask:0xf bound_ctrl:1
	v_mov_b32_dpp v215, v95 row_shl:14 row_mask:0xf bank_mask:0xf bound_ctrl:1
	v_mov_b32_dpp v222, v96 row_shl:14 row_mask:0xf bank_mask:0xf bound_ctrl:1
	v_mov_b32_dpp v223, v97 row_shl:14 row_mask:0xf bank_mask:0xf bound_ctrl:1
	v_pk_fma_f32 v[206:207], v[108:109], v[140:141], v[206:207]
	v_pk_fma_f32 v[168:169], v[134:135], v[204:205], v[168:169]
	v_mov_b32_dpp v224, v78 row_shr:2 row_mask:0xf bank_mask:0xf bound_ctrl:1
	v_mov_b32_dpp v225, v79 row_shr:2 row_mask:0xf bank_mask:0xf bound_ctrl:1
	v_mov_b32_dpp v228, v80 row_shr:2 row_mask:0xf bank_mask:0xf bound_ctrl:1
	v_mov_b32_dpp v229, v81 row_shr:2 row_mask:0xf bank_mask:0xf bound_ctrl:1
	v_pk_mul_f32 v[212:213], v[154:155], v[212:213]
	v_pk_mul_f32 v[220:221], v[156:157], v[220:221]
	v_pk_fma_f32 v[204:205], v[136:137], v[208:209], v[206:207]
	v_pk_add_f32 v[168:169], v[130:131], v[168:169]
	v_pk_add_f32 v[218:219], v[222:223], v[228:229]
	v_pk_add_f32 v[214:215], v[214:215], v[224:225]
	v_pk_fma_f32 v[220:221], v[80:81], v[160:161], v[220:221]
	v_pk_fma_f32 v[212:213], v[78:79], v[158:159], v[212:213]
	v_pk_add_f32 v[216:217], v[132:133], v[204:205]
	v_pk_fma_f32 v[212:213], v[146:147], v[214:215], v[212:213]
	v_pk_fma_f32 v[214:215], v[148:149], v[218:219], v[220:221]
	v_mul_f32_e32 v218, 0xbfb8aa3b, v168
	v_mul_f32_e32 v219, 0xbfb8aa3b, v169
	v_exp_f32_e32 v218, v218
	v_exp_f32_e32 v219, v219
	v_mul_f32_e32 v220, 0xbfb8aa3b, v216
	v_mul_f32_e32 v221, 0xbfb8aa3b, v217
	v_exp_f32_e32 v220, v220
	v_exp_f32_e32 v221, v221
	v_add_f32_e32 v218, 1.0, v218
	v_add_f32_e32 v219, 1.0, v219
	v_rcp_f32_e32 v218, v218
	v_rcp_f32_e32 v219, v219
	v_add_f32_e32 v220, 1.0, v220
	v_add_f32_e32 v221, 1.0, v221
	v_rcp_f32_e32 v220, v220
	v_rcp_f32_e32 v221, v221
	v_pk_add_f32 v[212:213], v[150:151], v[212:213]
	v_pk_mul_f32 v[168:169], v[168:169], v[218:219]
	v_pk_add_f32 v[214:215], v[152:153], v[214:215]
	v_pk_mul_f32 v[168:169], v[168:169], v[212:213]
	v_pk_mul_f32 v[212:213], v[216:217], v[220:221]
	v_cvt_pk_bf16_f32 v168, v168, v169
	v_pk_mul_f32 v[212:213], v[212:213], v[214:215]
	v_mov_b32_dpp v198, v106 row_shl:15 row_mask:0xf bank_mask:0xf bound_ctrl:1
	v_cvt_pk_bf16_f32 v169, v212, v213
	v_or_b32_e32 v212, 32, v243
	v_mad_i64_i32 v[194:195], s[46:47], v212, s72, v[194:195]
	v_lshl_add_u64 v[194:195], v[194:195], 0, v[196:197]
	global_store_dwordx2 v[194:195], v[168:169], off
	v_lshl_add_u64 v[168:169], s[26:27], 0, v[188:189]
	v_mov_b32_dpp v190, v106 row_shl:14 row_mask:0xf bank_mask:0xf bound_ctrl:1
	v_mov_b32_dpp v199, v107 row_shl:15 row_mask:0xf bank_mask:0xf bound_ctrl:1
	v_mov_b32_dpp v191, v107 row_shl:14 row_mask:0xf bank_mask:0xf bound_ctrl:1
	v_mov_b32_dpp v202, v108 row_shl:15 row_mask:0xf bank_mask:0xf bound_ctrl:1
	v_mov_b32_dpp v200, v108 row_shl:14 row_mask:0xf bank_mask:0xf bound_ctrl:1
	v_mov_b32_dpp v203, v109 row_shl:15 row_mask:0xf bank_mask:0xf bound_ctrl:1
	v_mov_b32_dpp v201, v109 row_shl:14 row_mask:0xf bank_mask:0xf bound_ctrl:1
	v_mov_b32_dpp v206, v78 row_shl:15 row_mask:0xf bank_mask:0xf bound_ctrl:1
	v_mov_b32_dpp v204, v78 row_shl:14 row_mask:0xf bank_mask:0xf bound_ctrl:1
	v_mov_b32_dpp v207, v79 row_shl:15 row_mask:0xf bank_mask:0xf bound_ctrl:1
	v_mov_b32_dpp v205, v79 row_shl:14 row_mask:0xf bank_mask:0xf bound_ctrl:1
	v_mov_b32_dpp v210, v80 row_shl:15 row_mask:0xf bank_mask:0xf bound_ctrl:1
	v_mov_b32_dpp v208, v80 row_shl:14 row_mask:0xf bank_mask:0xf bound_ctrl:1
	v_mov_b32_dpp v211, v81 row_shl:15 row_mask:0xf bank_mask:0xf bound_ctrl:1
	v_mov_b32_dpp v209, v81 row_shl:14 row_mask:0xf bank_mask:0xf bound_ctrl:1
	v_mov_b32_dpp v216, v90 row_shr:1 row_mask:0xf bank_mask:0xf bound_ctrl:1
	v_mov_b32_dpp v212, v90 row_shr:2 row_mask:0xf bank_mask:0xf bound_ctrl:1
	v_mov_b32_dpp v217, v91 row_shr:1 row_mask:0xf bank_mask:0xf bound_ctrl:1
	v_mov_b32_dpp v213, v91 row_shr:2 row_mask:0xf bank_mask:0xf bound_ctrl:1
	v_mov_b32_dpp v218, v92 row_shr:1 row_mask:0xf bank_mask:0xf bound_ctrl:1
	v_mov_b32_dpp v214, v92 row_shr:2 row_mask:0xf bank_mask:0xf bound_ctrl:1
	v_mov_b32_dpp v219, v93 row_shr:1 row_mask:0xf bank_mask:0xf bound_ctrl:1
	v_mov_b32_dpp v215, v93 row_shr:2 row_mask:0xf bank_mask:0xf bound_ctrl:1
	v_lshl_add_u64 v[188:189], v[176:177], 2, v[168:169]
	s_and_saveexec_b64 s[46:47], s[6:7]
	s_cbranch_execz .LBB0_1108
.LBB0_1108:
	s_or_b64 exec, exec, s[46:47]
	v_mov_b32_dpp v224, v70 row_shr:1 row_mask:0xf bank_mask:0xf bound_ctrl:1
	v_mov_b32_dpp v220, v70 row_shr:2 row_mask:0xf bank_mask:0xf bound_ctrl:1
	v_mov_b32_dpp v225, v71 row_shr:1 row_mask:0xf bank_mask:0xf bound_ctrl:1
	v_mov_b32_dpp v221, v71 row_shr:2 row_mask:0xf bank_mask:0xf bound_ctrl:1
	v_mov_b32_dpp v226, v72 row_shr:1 row_mask:0xf bank_mask:0xf bound_ctrl:1
	v_mov_b32_dpp v222, v72 row_shr:2 row_mask:0xf bank_mask:0xf bound_ctrl:1
	v_mov_b32_dpp v227, v73 row_shr:1 row_mask:0xf bank_mask:0xf bound_ctrl:1
	v_mov_b32_dpp v223, v73 row_shr:2 row_mask:0xf bank_mask:0xf bound_ctrl:1
	s_and_saveexec_b64 s[46:47], s[6:7]
	s_cbranch_execz .LBB0_1110
	v_add_co_u32_e32 v168, vcc, 0x5000, v188
	s_nop 1
	v_addc_co_u32_e32 v169, vcc, 0, v189, vcc
.LBB0_1110:
	s_or_b64 exec, exec, s[46:47]
	v_pk_add_f32 v[202:203], v[202:203], v[218:219]
	v_pk_add_f32 v[198:199], v[198:199], v[216:217]
	v_pk_mul_f32 v[202:203], v[144:145], v[202:203]
	v_pk_mul_f32 v[198:199], v[142:143], v[198:199]
	v_pk_add_f32 v[200:201], v[200:201], v[214:215]
	v_pk_add_f32 v[190:191], v[190:191], v[212:213]
	v_pk_fma_f32 v[202:203], v[92:93], v[140:141], v[202:203]
	v_pk_fma_f32 v[198:199], v[90:91], v[138:139], v[198:199]
	v_pk_add_f32 v[168:169], v[210:211], v[226:227]
	v_pk_fma_f32 v[190:191], v[134:135], v[190:191], v[198:199]
	v_pk_fma_f32 v[198:199], v[136:137], v[200:201], v[202:203]
	v_pk_add_f32 v[190:191], v[130:131], v[190:191]
	v_pk_add_f32 v[198:199], v[132:133], v[198:199]
	v_mul_f32_e32 v200, 0xbfb8aa3b, v190
	v_mul_f32_e32 v201, 0xbfb8aa3b, v191
	v_mul_f32_e32 v202, 0xbfb8aa3b, v198
	v_mul_f32_e32 v203, 0xbfb8aa3b, v199
	v_exp_f32_e32 v200, v200
	v_exp_f32_e32 v201, v201
	v_exp_f32_e32 v202, v202
	v_exp_f32_e32 v203, v203
	v_add_f32_e32 v200, 1.0, v200
	v_add_f32_e32 v201, 1.0, v201
	v_add_f32_e32 v202, 1.0, v202
	v_add_f32_e32 v203, 1.0, v203
	v_pk_add_f32 v[206:207], v[206:207], v[224:225]
	v_rcp_f32_e32 v200, v200
	v_rcp_f32_e32 v201, v201
	v_rcp_f32_e32 v202, v202
	v_rcp_f32_e32 v203, v203
	v_pk_mul_f32 v[206:207], v[154:155], v[206:207]
	v_pk_mul_f32 v[168:169], v[156:157], v[168:169]
	v_pk_add_f32 v[208:209], v[208:209], v[222:223]
	v_pk_add_f32 v[204:205], v[204:205], v[220:221]
	v_pk_fma_f32 v[168:169], v[72:73], v[160:161], v[168:169]
	v_pk_fma_f32 v[206:207], v[70:71], v[158:159], v[206:207]
	v_pk_fma_f32 v[168:169], v[148:149], v[208:209], v[168:169]
	v_pk_fma_f32 v[204:205], v[146:147], v[204:205], v[206:207]
	v_pk_add_f32 v[168:169], v[152:153], v[168:169]
	v_pk_add_f32 v[204:205], v[150:151], v[204:205]
	v_pk_mul_f32 v[190:191], v[190:191], v[200:201]
	v_pk_mul_f32 v[198:199], v[198:199], v[202:203]
	v_pk_mul_f32 v[190:191], v[190:191], v[204:205]
	v_pk_mul_f32 v[168:169], v[198:199], v[168:169]
	v_cvt_pk_bf16_f32 v190, v190, v191
	v_cvt_pk_bf16_f32 v191, v168, v169
	v_or_b32_e32 v198, 48, v243
	v_mov_b64_e32 v[168:169], s[22:23]
	s_add_i32 s41, s39, 2
	v_mad_i64_i32 v[168:169], s[46:47], v198, s72, v[168:169]
	s_lshl_b32 s39, s41, 1
	v_lshl_add_u64 v[198:199], v[176:177], 1, v[168:169]
	v_add_u32_e32 v168, s39, v1
	v_mad_i64_i32 v[168:169], s[46:47], v168, s71, 0
	v_lshl_add_u64 v[168:169], s[24:25], 0, v[168:169]
	global_store_dwordx2 v[198:199], v[190:191], off
	v_mov_b32_dpp v218, v62 row_shr:1 row_mask:0xf bank_mask:0xf bound_ctrl:1
	v_mov_b32_dpp v204, v62 row_shr:2 row_mask:0xf bank_mask:0xf bound_ctrl:1
	v_mov_b32_dpp v212, v62 row_shl:15 row_mask:0xf bank_mask:0xf bound_ctrl:1
	v_mov_b32_dpp v210, v62 row_shl:14 row_mask:0xf bank_mask:0xf bound_ctrl:1
	v_mov_b32_dpp v219, v63 row_shr:1 row_mask:0xf bank_mask:0xf bound_ctrl:1
	v_mov_b32_dpp v205, v63 row_shr:2 row_mask:0xf bank_mask:0xf bound_ctrl:1
	v_mov_b32_dpp v213, v63 row_shl:15 row_mask:0xf bank_mask:0xf bound_ctrl:1
	v_mov_b32_dpp v211, v63 row_shl:14 row_mask:0xf bank_mask:0xf bound_ctrl:1
	v_mov_b32_dpp v222, v64 row_shr:1 row_mask:0xf bank_mask:0xf bound_ctrl:1
	v_mov_b32_dpp v220, v64 row_shr:2 row_mask:0xf bank_mask:0xf bound_ctrl:1
	v_mov_b32_dpp v216, v64 row_shl:15 row_mask:0xf bank_mask:0xf bound_ctrl:1
	v_mov_b32_dpp v214, v64 row_shl:14 row_mask:0xf bank_mask:0xf bound_ctrl:1
	v_mov_b32_dpp v223, v65 row_shr:1 row_mask:0xf bank_mask:0xf bound_ctrl:1
	v_mov_b32_dpp v221, v65 row_shr:2 row_mask:0xf bank_mask:0xf bound_ctrl:1
	v_mov_b32_dpp v217, v65 row_shl:15 row_mask:0xf bank_mask:0xf bound_ctrl:1
	v_mov_b32_dpp v215, v65 row_shl:14 row_mask:0xf bank_mask:0xf bound_ctrl:1
	v_lshl_add_u64 v[190:191], v[176:177], 2, v[168:169]
	s_and_saveexec_b64 s[46:47], s[4:5]
	s_cbranch_execz .LBB0_1112
.LBB0_1112:
	s_or_b64 exec, exec, s[46:47]
	v_mov_b32_dpp v226, v46 row_shr:1 row_mask:0xf bank_mask:0xf bound_ctrl:1
	v_mov_b32_dpp v224, v46 row_shr:2 row_mask:0xf bank_mask:0xf bound_ctrl:1
	v_mov_b32_dpp v202, v46 row_shl:15 row_mask:0xf bank_mask:0xf bound_ctrl:1
	v_mov_b32_dpp v200, v46 row_shl:14 row_mask:0xf bank_mask:0xf bound_ctrl:1
	v_mov_b32_dpp v227, v47 row_shr:1 row_mask:0xf bank_mask:0xf bound_ctrl:1
	v_mov_b32_dpp v225, v47 row_shr:2 row_mask:0xf bank_mask:0xf bound_ctrl:1
	v_mov_b32_dpp v203, v47 row_shl:15 row_mask:0xf bank_mask:0xf bound_ctrl:1
	v_mov_b32_dpp v201, v47 row_shl:14 row_mask:0xf bank_mask:0xf bound_ctrl:1
	v_mov_b32_dpp v230, v48 row_shr:1 row_mask:0xf bank_mask:0xf bound_ctrl:1
	v_mov_b32_dpp v228, v48 row_shr:2 row_mask:0xf bank_mask:0xf bound_ctrl:1
	v_mov_b32_dpp v208, v48 row_shl:15 row_mask:0xf bank_mask:0xf bound_ctrl:1
	v_mov_b32_dpp v206, v48 row_shl:14 row_mask:0xf bank_mask:0xf bound_ctrl:1
	v_mov_b32_dpp v231, v49 row_shr:1 row_mask:0xf bank_mask:0xf bound_ctrl:1
	v_mov_b32_dpp v229, v49 row_shr:2 row_mask:0xf bank_mask:0xf bound_ctrl:1
	v_mov_b32_dpp v209, v49 row_shl:15 row_mask:0xf bank_mask:0xf bound_ctrl:1
	v_mov_b32_dpp v207, v49 row_shl:14 row_mask:0xf bank_mask:0xf bound_ctrl:1
	s_and_saveexec_b64 s[46:47], s[4:5]
	s_cbranch_execz .LBB0_1114
	v_add_co_u32_e32 v168, vcc, 0x5000, v190
	s_nop 1
	v_addc_co_u32_e32 v169, vcc, 0, v191, vcc
.LBB0_1114:
	s_or_b64 exec, exec, s[46:47]
	v_lshl_or_b32 v244, s41, 6, v1
	s_and_saveexec_b64 s[46:47], s[8:9]
	s_cbranch_execz .LBB0_1116
	v_pk_add_f32 v[218:219], v[218:219], 0 op_sel_hi:[1,0]
	v_pk_add_f32 v[222:223], v[222:223], 0 op_sel_hi:[1,0]
	v_pk_mul_f32 v[218:219], v[142:143], v[218:219]
	v_pk_add_f32 v[204:205], v[204:205], 0 op_sel_hi:[1,0]
	v_pk_mul_f32 v[222:223], v[144:145], v[222:223]
	v_pk_fma_f32 v[218:219], v[62:63], v[138:139], v[218:219]
	v_pk_add_f32 v[220:221], v[220:221], 0 op_sel_hi:[1,0]
	v_pk_fma_f32 v[222:223], v[64:65], v[140:141], v[222:223]
	v_pk_fma_f32 v[204:205], v[134:135], v[204:205], v[218:219]
	v_pk_fma_f32 v[218:219], v[136:137], v[220:221], v[222:223]
	v_pk_add_f32 v[204:205], v[130:131], v[204:205]
	v_pk_add_f32 v[218:219], v[132:133], v[218:219]
	v_mul_f32_e32 v220, 0xbfb8aa3b, v204
	v_mul_f32_e32 v221, 0xbfb8aa3b, v205
	v_exp_f32_e32 v220, v220
	v_exp_f32_e32 v221, v221
	v_mul_f32_e32 v222, 0xbfb8aa3b, v218
	v_mul_f32_e32 v223, 0xbfb8aa3b, v219
	v_exp_f32_e32 v222, v222
	v_exp_f32_e32 v223, v223
	v_add_f32_e32 v220, 1.0, v220
	v_add_f32_e32 v221, 1.0, v221
	v_pk_add_f32 v[168:169], v[226:227], 0 op_sel_hi:[1,0]
	v_rcp_f32_e32 v220, v220
	v_rcp_f32_e32 v221, v221
	v_add_f32_e32 v222, 1.0, v222
	v_add_f32_e32 v223, 1.0, v223
	v_pk_add_f32 v[226:227], v[230:231], 0 op_sel_hi:[1,0]
	v_pk_mul_f32 v[168:169], v[154:155], v[168:169]
	v_rcp_f32_e32 v222, v222
	v_rcp_f32_e32 v223, v223
	v_pk_add_f32 v[224:225], v[224:225], 0 op_sel_hi:[1,0]
	v_pk_mul_f32 v[226:227], v[156:157], v[226:227]
	v_pk_fma_f32 v[168:169], v[46:47], v[158:159], v[168:169]
	v_pk_add_f32 v[228:229], v[228:229], 0 op_sel_hi:[1,0]
	v_pk_fma_f32 v[226:227], v[48:49], v[160:161], v[226:227]
	v_pk_fma_f32 v[168:169], v[146:147], v[224:225], v[168:169]
	v_pk_fma_f32 v[224:225], v[148:149], v[228:229], v[226:227]
	v_pk_add_f32 v[168:169], v[150:151], v[168:169]
	v_pk_mul_f32 v[204:205], v[204:205], v[220:221]
	v_pk_add_f32 v[224:225], v[152:153], v[224:225]
	v_pk_mul_f32 v[168:169], v[204:205], v[168:169]
	v_pk_mul_f32 v[204:205], v[218:219], v[222:223]
	v_cvt_pk_bf16_f32 v168, v168, v169
	v_pk_mul_f32 v[204:205], v[204:205], v[224:225]
	s_nop 0
	v_cvt_pk_bf16_f32 v169, v204, v205
	v_mov_b64_e32 v[204:205], s[22:23]
	v_mad_i64_i32 v[204:205], s[48:49], v244, s72, v[204:205]
	v_lshl_add_u64 v[204:205], v[176:177], 1, v[204:205]
	global_store_dwordx2 v[204:205], v[168:169], off
.LBB0_1116:
	s_or_b64 exec, exec, s[46:47]
	v_add_u32_e32 v168, s39, v237
	v_mad_i64_i32 v[204:205], s[46:47], v168, s71, 0
	s_nop 0
	v_mov_b32_dpp v168, v54 row_shr:1 row_mask:0xf bank_mask:0xf bound_ctrl:1
	v_mov_b32_dpp v169, v55 row_shr:1 row_mask:0xf bank_mask:0xf bound_ctrl:1
	v_mov_b32_dpp v224, v56 row_shr:1 row_mask:0xf bank_mask:0xf bound_ctrl:1
	v_mov_b32_dpp v225, v57 row_shr:1 row_mask:0xf bank_mask:0xf bound_ctrl:1
	v_mov_b32_dpp v226, v56 row_shr:2 row_mask:0xf bank_mask:0xf bound_ctrl:1
	v_pk_add_f32 v[216:217], v[216:217], v[224:225]
	v_pk_add_f32 v[168:169], v[212:213], v[168:169]
	v_mov_b32_dpp v227, v57 row_shr:2 row_mask:0xf bank_mask:0xf bound_ctrl:1
	v_mov_b32_dpp v218, v54 row_shr:2 row_mask:0xf bank_mask:0xf bound_ctrl:1
	v_mov_b32_dpp v219, v55 row_shr:2 row_mask:0xf bank_mask:0xf bound_ctrl:1
	v_pk_add_f32 v[212:213], v[214:215], v[226:227]
	v_pk_mul_f32 v[168:169], v[142:143], v[168:169]
	v_pk_mul_f32 v[214:215], v[144:145], v[216:217]
	v_pk_add_f32 v[210:211], v[210:211], v[218:219]
	v_pk_fma_f32 v[214:215], v[56:57], v[140:141], v[214:215]
	v_pk_fma_f32 v[168:169], v[54:55], v[138:139], v[168:169]
	v_mov_b32_dpp v216, v32 row_shr:1 row_mask:0xf bank_mask:0xf bound_ctrl:1
	v_pk_fma_f32 v[168:169], v[134:135], v[210:211], v[168:169]
	v_pk_fma_f32 v[210:211], v[136:137], v[212:213], v[214:215]
	v_mov_b32_dpp v212, v30 row_shr:1 row_mask:0xf bank_mask:0xf bound_ctrl:1
	v_mov_b32_dpp v213, v31 row_shr:1 row_mask:0xf bank_mask:0xf bound_ctrl:1
	v_mov_b32_dpp v217, v33 row_shr:1 row_mask:0xf bank_mask:0xf bound_ctrl:1
	v_pk_add_f32 v[208:209], v[208:209], v[216:217]
	v_pk_add_f32 v[202:203], v[202:203], v[212:213]
	v_mov_b32_dpp v214, v30 row_shr:2 row_mask:0xf bank_mask:0xf bound_ctrl:1
	v_mov_b32_dpp v215, v31 row_shr:2 row_mask:0xf bank_mask:0xf bound_ctrl:1
	v_mov_b32_dpp v218, v32 row_shr:2 row_mask:0xf bank_mask:0xf bound_ctrl:1
	v_mov_b32_dpp v219, v33 row_shr:2 row_mask:0xf bank_mask:0xf bound_ctrl:1
	v_pk_mul_f32 v[202:203], v[154:155], v[202:203]
	v_pk_mul_f32 v[208:209], v[156:157], v[208:209]
	v_pk_add_f32 v[168:169], v[130:131], v[168:169]
	v_pk_add_f32 v[206:207], v[206:207], v[218:219]
	v_pk_add_f32 v[200:201], v[200:201], v[214:215]
	v_pk_fma_f32 v[208:209], v[32:33], v[160:161], v[208:209]
	v_pk_fma_f32 v[202:203], v[30:31], v[158:159], v[202:203]
	v_pk_add_f32 v[210:211], v[132:133], v[210:211]
	v_pk_fma_f32 v[200:201], v[146:147], v[200:201], v[202:203]
	v_pk_fma_f32 v[202:203], v[148:149], v[206:207], v[208:209]
	v_mul_f32_e32 v206, 0xbfb8aa3b, v168
	v_mul_f32_e32 v207, 0xbfb8aa3b, v169
	v_exp_f32_e32 v206, v206
	v_exp_f32_e32 v207, v207
	v_mul_f32_e32 v208, 0xbfb8aa3b, v210
	v_mul_f32_e32 v209, 0xbfb8aa3b, v211
	v_exp_f32_e32 v208, v208
	v_exp_f32_e32 v209, v209
	v_add_f32_e32 v206, 1.0, v206
	v_add_f32_e32 v207, 1.0, v207
	v_rcp_f32_e32 v206, v206
	v_rcp_f32_e32 v207, v207
	v_add_f32_e32 v208, 1.0, v208
	v_add_f32_e32 v209, 1.0, v209
	v_rcp_f32_e32 v208, v208
	v_rcp_f32_e32 v209, v209
	v_pk_add_f32 v[200:201], v[150:151], v[200:201]
	v_pk_mul_f32 v[168:169], v[168:169], v[206:207]
	v_pk_add_f32 v[202:203], v[152:153], v[202:203]
	v_pk_mul_f32 v[168:169], v[168:169], v[200:201]
	v_pk_mul_f32 v[200:201], v[210:211], v[208:209]
	v_cvt_pk_bf16_f32 v168, v168, v169
	v_pk_mul_f32 v[200:201], v[200:201], v[202:203]
	v_mov_b64_e32 v[202:203], s[22:23]
	v_cvt_pk_bf16_f32 v169, v200, v201
	v_or_b32_e32 v200, 16, v244
	v_mad_i64_i32 v[200:201], s[46:47], v200, s72, v[202:203]
	v_lshl_add_u64 v[200:201], v[200:201], 0, v[196:197]
	v_mov_b32_dpp v220, v54 row_shl:15 row_mask:0xf bank_mask:0xf bound_ctrl:1
	v_mov_b32_dpp v221, v55 row_shl:15 row_mask:0xf bank_mask:0xf bound_ctrl:1
	v_mov_b32_dpp v228, v56 row_shl:15 row_mask:0xf bank_mask:0xf bound_ctrl:1
	v_mov_b32_dpp v229, v57 row_shl:15 row_mask:0xf bank_mask:0xf bound_ctrl:1
	global_store_dwordx2 v[200:201], v[168:169], off
	v_mov_b32_dpp v168, v42 row_shr:1 row_mask:0xf bank_mask:0xf bound_ctrl:1
	v_mov_b32_dpp v169, v43 row_shr:1 row_mask:0xf bank_mask:0xf bound_ctrl:1
	v_mov_b32_dpp v216, v44 row_shr:1 row_mask:0xf bank_mask:0xf bound_ctrl:1
	v_mov_b32_dpp v217, v45 row_shr:1 row_mask:0xf bank_mask:0xf bound_ctrl:1
	v_pk_add_f32 v[216:217], v[228:229], v[216:217]
	v_pk_add_f32 v[168:169], v[220:221], v[168:169]
	v_mov_b32_dpp v222, v54 row_shl:14 row_mask:0xf bank_mask:0xf bound_ctrl:1
	v_mov_b32_dpp v223, v55 row_shl:14 row_mask:0xf bank_mask:0xf bound_ctrl:1
	v_mov_b32_dpp v230, v56 row_shl:14 row_mask:0xf bank_mask:0xf bound_ctrl:1
	v_mov_b32_dpp v231, v57 row_shl:14 row_mask:0xf bank_mask:0xf bound_ctrl:1
	v_mov_b32_dpp v224, v30 row_shl:15 row_mask:0xf bank_mask:0xf bound_ctrl:1
	v_mov_b32_dpp v225, v31 row_shl:15 row_mask:0xf bank_mask:0xf bound_ctrl:1
	v_mov_b32_dpp v232, v32 row_shl:15 row_mask:0xf bank_mask:0xf bound_ctrl:1
	v_mov_b32_dpp v233, v33 row_shl:15 row_mask:0xf bank_mask:0xf bound_ctrl:1
	v_mov_b32_dpp v214, v42 row_shr:2 row_mask:0xf bank_mask:0xf bound_ctrl:1
	v_mov_b32_dpp v215, v43 row_shr:2 row_mask:0xf bank_mask:0xf bound_ctrl:1
	v_mov_b32_dpp v218, v44 row_shr:2 row_mask:0xf bank_mask:0xf bound_ctrl:1
	v_mov_b32_dpp v219, v45 row_shr:2 row_mask:0xf bank_mask:0xf bound_ctrl:1
	v_pk_mul_f32 v[168:169], v[142:143], v[168:169]
	v_pk_mul_f32 v[216:217], v[144:145], v[216:217]
	v_mov_b32_dpp v228, v14 row_shr:1 row_mask:0xf bank_mask:0xf bound_ctrl:1
	v_mov_b32_dpp v229, v15 row_shr:1 row_mask:0xf bank_mask:0xf bound_ctrl:1
	v_mov_b32_dpp v246, v16 row_shr:1 row_mask:0xf bank_mask:0xf bound_ctrl:1
	v_mov_b32_dpp v247, v17 row_shr:1 row_mask:0xf bank_mask:0xf bound_ctrl:1
	v_mov_b32_dpp v226, v30 row_shl:14 row_mask:0xf bank_mask:0xf bound_ctrl:1
	v_mov_b32_dpp v227, v31 row_shl:14 row_mask:0xf bank_mask:0xf bound_ctrl:1
	v_pk_add_f32 v[218:219], v[230:231], v[218:219]
	v_pk_add_f32 v[214:215], v[222:223], v[214:215]
	v_pk_fma_f32 v[216:217], v[44:45], v[140:141], v[216:217]
	v_pk_fma_f32 v[168:169], v[42:43], v[138:139], v[168:169]
	v_mov_b32_dpp v230, v14 row_shr:2 row_mask:0xf bank_mask:0xf bound_ctrl:1
	v_mov_b32_dpp v231, v15 row_shr:2 row_mask:0xf bank_mask:0xf bound_ctrl:1
	v_pk_add_f32 v[232:233], v[232:233], v[246:247]
	v_pk_add_f32 v[224:225], v[224:225], v[228:229]
	v_mov_b32_dpp v234, v32 row_shl:14 row_mask:0xf bank_mask:0xf bound_ctrl:1
	v_mov_b32_dpp v235, v33 row_shl:14 row_mask:0xf bank_mask:0xf bound_ctrl:1
	v_pk_fma_f32 v[168:169], v[134:135], v[214:215], v[168:169]
	v_pk_fma_f32 v[214:215], v[136:137], v[218:219], v[216:217]
	v_mov_b32_dpp v248, v16 row_shr:2 row_mask:0xf bank_mask:0xf bound_ctrl:1
	v_mov_b32_dpp v249, v17 row_shr:2 row_mask:0xf bank_mask:0xf bound_ctrl:1
	v_pk_add_f32 v[226:227], v[226:227], v[230:231]
	v_pk_mul_f32 v[224:225], v[154:155], v[224:225]
	v_pk_mul_f32 v[230:231], v[156:157], v[232:233]
	v_pk_add_f32 v[222:223], v[132:133], v[214:215]
	v_pk_add_f32 v[168:169], v[130:131], v[168:169]
	v_pk_add_f32 v[228:229], v[234:235], v[248:249]
	v_pk_fma_f32 v[230:231], v[16:17], v[160:161], v[230:231]
	v_pk_fma_f32 v[224:225], v[14:15], v[158:159], v[224:225]
	v_mov_b32_dpp v208, v42 row_shl:15 row_mask:0xf bank_mask:0xf bound_ctrl:1
	v_pk_fma_f32 v[224:225], v[146:147], v[226:227], v[224:225]
	v_pk_fma_f32 v[226:227], v[148:149], v[228:229], v[230:231]
	v_mul_f32_e32 v228, 0xbfb8aa3b, v168
	v_mul_f32_e32 v229, 0xbfb8aa3b, v169
	v_mul_f32_e32 v230, 0xbfb8aa3b, v222
	v_mul_f32_e32 v231, 0xbfb8aa3b, v223
	v_exp_f32_e32 v228, v228
	v_exp_f32_e32 v229, v229
	v_exp_f32_e32 v230, v230
	v_exp_f32_e32 v231, v231
	v_add_f32_e32 v228, 1.0, v228
	v_add_f32_e32 v229, 1.0, v229
	v_add_f32_e32 v230, 1.0, v230
	v_add_f32_e32 v231, 1.0, v231
	v_rcp_f32_e32 v228, v228
	v_rcp_f32_e32 v229, v229
	v_rcp_f32_e32 v230, v230
	v_rcp_f32_e32 v231, v231
	v_pk_add_f32 v[226:227], v[152:153], v[226:227]
	v_pk_add_f32 v[224:225], v[150:151], v[224:225]
	v_pk_mul_f32 v[168:169], v[168:169], v[228:229]
	v_pk_mul_f32 v[222:223], v[222:223], v[230:231]
	v_pk_mul_f32 v[168:169], v[168:169], v[224:225]
	v_pk_mul_f32 v[222:223], v[222:223], v[226:227]
	v_cvt_pk_bf16_f32 v168, v168, v169
	v_cvt_pk_bf16_f32 v169, v222, v223
	v_or_b32_e32 v222, 32, v244
	v_mad_i64_i32 v[202:203], s[46:47], v222, s72, v[202:203]
	v_lshl_add_u64 v[202:203], v[202:203], 0, v[196:197]
	global_store_dwordx2 v[202:203], v[168:169], off
	v_lshl_add_u64 v[168:169], s[26:27], 0, v[204:205]
	v_mov_b32_dpp v206, v42 row_shl:14 row_mask:0xf bank_mask:0xf bound_ctrl:1
	v_mov_b32_dpp v209, v43 row_shl:15 row_mask:0xf bank_mask:0xf bound_ctrl:1
	v_mov_b32_dpp v207, v43 row_shl:14 row_mask:0xf bank_mask:0xf bound_ctrl:1
	v_mov_b32_dpp v212, v44 row_shl:15 row_mask:0xf bank_mask:0xf bound_ctrl:1
	v_mov_b32_dpp v210, v44 row_shl:14 row_mask:0xf bank_mask:0xf bound_ctrl:1
	v_mov_b32_dpp v213, v45 row_shl:15 row_mask:0xf bank_mask:0xf bound_ctrl:1
	v_mov_b32_dpp v211, v45 row_shl:14 row_mask:0xf bank_mask:0xf bound_ctrl:1
	v_mov_b32_dpp v216, v14 row_shl:15 row_mask:0xf bank_mask:0xf bound_ctrl:1
	v_mov_b32_dpp v214, v14 row_shl:14 row_mask:0xf bank_mask:0xf bound_ctrl:1
	v_mov_b32_dpp v217, v15 row_shl:15 row_mask:0xf bank_mask:0xf bound_ctrl:1
	v_mov_b32_dpp v215, v15 row_shl:14 row_mask:0xf bank_mask:0xf bound_ctrl:1
	v_mov_b32_dpp v220, v16 row_shl:15 row_mask:0xf bank_mask:0xf bound_ctrl:1
	v_mov_b32_dpp v218, v16 row_shl:14 row_mask:0xf bank_mask:0xf bound_ctrl:1
	v_mov_b32_dpp v221, v17 row_shl:15 row_mask:0xf bank_mask:0xf bound_ctrl:1
	v_mov_b32_dpp v219, v17 row_shl:14 row_mask:0xf bank_mask:0xf bound_ctrl:1
	v_mov_b32_dpp v226, v26 row_shr:1 row_mask:0xf bank_mask:0xf bound_ctrl:1
	v_mov_b32_dpp v222, v26 row_shr:2 row_mask:0xf bank_mask:0xf bound_ctrl:1
	v_mov_b32_dpp v227, v27 row_shr:1 row_mask:0xf bank_mask:0xf bound_ctrl:1
	v_mov_b32_dpp v223, v27 row_shr:2 row_mask:0xf bank_mask:0xf bound_ctrl:1
	v_mov_b32_dpp v228, v28 row_shr:1 row_mask:0xf bank_mask:0xf bound_ctrl:1
	v_mov_b32_dpp v224, v28 row_shr:2 row_mask:0xf bank_mask:0xf bound_ctrl:1
	v_mov_b32_dpp v229, v29 row_shr:1 row_mask:0xf bank_mask:0xf bound_ctrl:1
	v_mov_b32_dpp v225, v29 row_shr:2 row_mask:0xf bank_mask:0xf bound_ctrl:1
	v_lshl_add_u64 v[196:197], v[176:177], 2, v[168:169]
	s_and_saveexec_b64 s[46:47], s[6:7]
	s_cbranch_execz .LBB0_1118
.LBB0_1118:
	s_or_b64 exec, exec, s[46:47]
	v_mov_b32_dpp v232, v6 row_shr:1 row_mask:0xf bank_mask:0xf bound_ctrl:1
	v_mov_b32_dpp v204, v6 row_shr:2 row_mask:0xf bank_mask:0xf bound_ctrl:1
	v_mov_b32_dpp v233, v7 row_shr:1 row_mask:0xf bank_mask:0xf bound_ctrl:1
	v_mov_b32_dpp v205, v7 row_shr:2 row_mask:0xf bank_mask:0xf bound_ctrl:1
	v_mov_b32_dpp v234, v8 row_shr:1 row_mask:0xf bank_mask:0xf bound_ctrl:1
	v_mov_b32_dpp v230, v8 row_shr:2 row_mask:0xf bank_mask:0xf bound_ctrl:1
	v_mov_b32_dpp v235, v9 row_shr:1 row_mask:0xf bank_mask:0xf bound_ctrl:1
	v_mov_b32_dpp v231, v9 row_shr:2 row_mask:0xf bank_mask:0xf bound_ctrl:1
	s_and_saveexec_b64 s[46:47], s[6:7]
	s_cbranch_execz .LBB0_1120
	v_add_co_u32_e32 v168, vcc, 0x5000, v196
	s_nop 1
	v_addc_co_u32_e32 v169, vcc, 0, v197, vcc
.LBB0_1120:
	s_or_b64 exec, exec, s[46:47]
	v_pk_add_f32 v[168:169], v[220:221], v[234:235]
	v_pk_add_f32 v[216:217], v[216:217], v[232:233]
	v_pk_mul_f32 v[156:157], v[156:157], v[168:169]
	v_pk_mul_f32 v[154:155], v[154:155], v[216:217]
	v_pk_add_f32 v[218:219], v[218:219], v[230:231]
	v_pk_add_f32 v[204:205], v[214:215], v[204:205]
	v_pk_fma_f32 v[156:157], v[8:9], v[160:161], v[156:157]
	v_pk_fma_f32 v[154:155], v[6:7], v[158:159], v[154:155]
	v_pk_fma_f32 v[148:149], v[148:149], v[218:219], v[156:157]
	v_pk_fma_f32 v[146:147], v[146:147], v[204:205], v[154:155]
	v_pk_add_f32 v[148:149], v[152:153], v[148:149]
	v_pk_add_f32 v[146:147], v[150:151], v[146:147]
	v_pk_add_f32 v[150:151], v[212:213], v[228:229]
	v_pk_add_f32 v[152:153], v[208:209], v[226:227]
	v_pk_mul_f32 v[144:145], v[144:145], v[150:151]
	v_pk_mul_f32 v[142:143], v[142:143], v[152:153]
	v_pk_add_f32 v[154:155], v[210:211], v[224:225]
	v_pk_add_f32 v[156:157], v[206:207], v[222:223]
	v_pk_fma_f32 v[140:141], v[28:29], v[140:141], v[144:145]
	v_pk_fma_f32 v[138:139], v[26:27], v[138:139], v[142:143]
	v_pk_fma_f32 v[136:137], v[136:137], v[154:155], v[140:141]
	v_pk_fma_f32 v[134:135], v[134:135], v[156:157], v[138:139]
	v_pk_add_f32 v[132:133], v[132:133], v[136:137]
	v_pk_add_f32 v[130:131], v[130:131], v[134:135]
	v_mul_f32_e32 v136, 0xbfb8aa3b, v132
	v_mul_f32_e32 v134, 0xbfb8aa3b, v130
	v_mul_f32_e32 v135, 0xbfb8aa3b, v131
	v_mul_f32_e32 v137, 0xbfb8aa3b, v133
	v_exp_f32_e32 v134, v134
	v_exp_f32_e32 v135, v135
	v_exp_f32_e32 v136, v136
	v_exp_f32_e32 v137, v137
	v_add_f32_e32 v134, 1.0, v134
	v_add_f32_e32 v135, 1.0, v135
	v_add_f32_e32 v136, 1.0, v136
	v_add_f32_e32 v137, 1.0, v137
	v_rcp_f32_e32 v134, v134
	v_rcp_f32_e32 v135, v135
	v_rcp_f32_e32 v136, v136
	v_rcp_f32_e32 v137, v137
	v_mov_b32_dpp v216, v122 row_shr:1 row_mask:0xf bank_mask:0xf bound_ctrl:1
	v_pk_mul_f32 v[130:131], v[130:131], v[134:135]
	v_or_b32_e32 v134, 48, v244
	v_pk_mul_f32 v[132:133], v[132:133], v[136:137]
	v_pk_mul_f32 v[130:131], v[130:131], v[146:147]
	v_pk_mul_f32 v[132:133], v[132:133], v[148:149]
	v_cvt_pk_bf16_f32 v130, v130, v131
	v_cvt_pk_bf16_f32 v131, v132, v133
	v_mov_b64_e32 v[132:133], s[22:23]
	v_mad_i64_i32 v[132:133], s[46:47], v134, s72, v[132:133]
	v_lshl_add_u64 v[204:205], v[176:177], 1, v[132:133]
	global_store_dwordx2 v[204:205], v[130:131], off
	v_or_b32_e32 v130, 16, v176
	v_add_co_u32_e32 v146, vcc, s70, v186
	v_ashrrev_i32_e32 v131, 31, v130
	s_nop 0
	v_addc_co_u32_e32 v147, vcc, 0, v187, vcc
	v_lshlrev_b64 v[130:131], 2, v[130:131]
	v_add_co_u32_e32 v150, vcc, s70, v184
	v_lshl_add_u64 v[132:133], s[30:31], 0, v[130:131]
	v_lshl_add_u64 v[130:131], s[34:35], 0, v[130:131]
	v_addc_co_u32_e32 v151, vcc, 0, v185, vcc
	global_load_dwordx4 v[134:137], v[186:187], off offset:64
	global_load_dwordx4 v[142:145], v[132:133], off
	global_load_dwordx4 v[138:141], v[130:131], off
	s_nop 0
	global_load_dwordx4 v[130:133], v[180:181], off offset:64
	s_nop 0
	global_load_dwordx4 v[146:149], v[146:147], off offset:2112
	s_nop 0
	global_load_dwordx4 v[158:161], v[150:151], off offset:2112
	v_add_co_u32_e32 v150, vcc, s70, v182
	v_mov_b32_dpp v214, v122 row_shr:2 row_mask:0xf bank_mask:0xf bound_ctrl:1
	s_nop 0
	v_addc_co_u32_e32 v151, vcc, 0, v183, vcc
	global_load_dwordx4 v[154:157], v[150:151], off offset:2112
	v_add_co_u32_e32 v150, vcc, s70, v180
	v_mov_b32_dpp v208, v122 row_shl:15 row_mask:0xf bank_mask:0xf bound_ctrl:1
	s_nop 0
	v_addc_co_u32_e32 v151, vcc, 0, v181, vcc
	global_load_dwordx4 v[150:153], v[150:151], off offset:2112
	v_mov_b32_dpp v206, v122 row_shl:14 row_mask:0xf bank_mask:0xf bound_ctrl:1
	v_mov_b32_dpp v217, v123 row_shr:1 row_mask:0xf bank_mask:0xf bound_ctrl:1
	v_mov_b32_dpp v215, v123 row_shr:2 row_mask:0xf bank_mask:0xf bound_ctrl:1
	v_mov_b32_dpp v209, v123 row_shl:15 row_mask:0xf bank_mask:0xf bound_ctrl:1
	v_mov_b32_dpp v207, v123 row_shl:14 row_mask:0xf bank_mask:0xf bound_ctrl:1
	v_mov_b32_dpp v220, v124 row_shr:1 row_mask:0xf bank_mask:0xf bound_ctrl:1
	v_mov_b32_dpp v218, v124 row_shr:2 row_mask:0xf bank_mask:0xf bound_ctrl:1
	v_mov_b32_dpp v212, v124 row_shl:15 row_mask:0xf bank_mask:0xf bound_ctrl:1
	v_mov_b32_dpp v210, v124 row_shl:14 row_mask:0xf bank_mask:0xf bound_ctrl:1
	v_mov_b32_dpp v221, v125 row_shr:1 row_mask:0xf bank_mask:0xf bound_ctrl:1
	v_mov_b32_dpp v219, v125 row_shr:2 row_mask:0xf bank_mask:0xf bound_ctrl:1
	v_mov_b32_dpp v213, v125 row_shl:15 row_mask:0xf bank_mask:0xf bound_ctrl:1
	v_mov_b32_dpp v211, v125 row_shl:14 row_mask:0xf bank_mask:0xf bound_ctrl:1
	s_and_saveexec_b64 s[46:47], s[4:5]
	s_cbranch_execz .LBB0_1122
.LBB0_1122:
	s_or_b64 exec, exec, s[46:47]
	v_mov_b32_dpp v224, v102 row_shr:1 row_mask:0xf bank_mask:0xf bound_ctrl:1
	v_mov_b32_dpp v222, v102 row_shr:2 row_mask:0xf bank_mask:0xf bound_ctrl:1
	v_mov_b32_dpp v182, v102 row_shl:15 row_mask:0xf bank_mask:0xf bound_ctrl:1
	v_mov_b32_dpp v180, v102 row_shl:14 row_mask:0xf bank_mask:0xf bound_ctrl:1
	v_mov_b32_dpp v225, v103 row_shr:1 row_mask:0xf bank_mask:0xf bound_ctrl:1
	v_mov_b32_dpp v223, v103 row_shr:2 row_mask:0xf bank_mask:0xf bound_ctrl:1
	v_mov_b32_dpp v183, v103 row_shl:15 row_mask:0xf bank_mask:0xf bound_ctrl:1
	v_mov_b32_dpp v181, v103 row_shl:14 row_mask:0xf bank_mask:0xf bound_ctrl:1
	v_mov_b32_dpp v228, v104 row_shr:1 row_mask:0xf bank_mask:0xf bound_ctrl:1
	v_mov_b32_dpp v226, v104 row_shr:2 row_mask:0xf bank_mask:0xf bound_ctrl:1
	v_mov_b32_dpp v186, v104 row_shl:15 row_mask:0xf bank_mask:0xf bound_ctrl:1
	v_mov_b32_dpp v184, v104 row_shl:14 row_mask:0xf bank_mask:0xf bound_ctrl:1
	v_mov_b32_dpp v229, v105 row_shr:1 row_mask:0xf bank_mask:0xf bound_ctrl:1
	v_mov_b32_dpp v227, v105 row_shr:2 row_mask:0xf bank_mask:0xf bound_ctrl:1
	v_mov_b32_dpp v187, v105 row_shl:15 row_mask:0xf bank_mask:0xf bound_ctrl:1
	v_mov_b32_dpp v185, v105 row_shl:14 row_mask:0xf bank_mask:0xf bound_ctrl:1
	s_and_saveexec_b64 s[46:47], s[4:5]
	s_cbranch_execz .LBB0_1124
	v_add_co_u32_e32 v168, vcc, 0x5000, v178
	s_nop 1
	v_addc_co_u32_e32 v169, vcc, 0, v179, vcc
.LBB0_1124:
	s_or_b64 exec, exec, s[46:47]
	s_and_saveexec_b64 s[46:47], s[8:9]
	s_cbranch_execz .LBB0_1126
	v_pk_add_f32 v[216:217], v[216:217], 0 op_sel_hi:[1,0]
	v_pk_add_f32 v[220:221], v[220:221], 0 op_sel_hi:[1,0]
	s_waitcnt vmcnt(0)
	v_pk_mul_f32 v[216:217], v[142:143], v[216:217]
	v_pk_add_f32 v[214:215], v[214:215], 0 op_sel_hi:[1,0]
	v_pk_mul_f32 v[220:221], v[144:145], v[220:221]
	v_pk_fma_f32 v[216:217], v[122:123], v[138:139], v[216:217]
	v_pk_add_f32 v[218:219], v[218:219], 0 op_sel_hi:[1,0]
	v_pk_fma_f32 v[220:221], v[124:125], v[140:141], v[220:221]
	v_pk_fma_f32 v[214:215], v[134:135], v[214:215], v[216:217]
	v_pk_fma_f32 v[216:217], v[136:137], v[218:219], v[220:221]
	v_pk_add_f32 v[214:215], v[130:131], v[214:215]
	v_pk_add_f32 v[216:217], v[132:133], v[216:217]
	v_mul_f32_e32 v218, 0xbfb8aa3b, v214
	v_mul_f32_e32 v219, 0xbfb8aa3b, v215
	v_exp_f32_e32 v218, v218
	v_exp_f32_e32 v219, v219
	v_mul_f32_e32 v220, 0xbfb8aa3b, v216
	v_mul_f32_e32 v221, 0xbfb8aa3b, v217
	v_exp_f32_e32 v220, v220
	v_exp_f32_e32 v221, v221
	v_add_f32_e32 v218, 1.0, v218
	v_add_f32_e32 v219, 1.0, v219
	v_pk_add_f32 v[168:169], v[224:225], 0 op_sel_hi:[1,0]
	v_rcp_f32_e32 v218, v218
	v_rcp_f32_e32 v219, v219
	v_add_f32_e32 v220, 1.0, v220
	v_add_f32_e32 v221, 1.0, v221
	v_pk_add_f32 v[178:179], v[228:229], 0 op_sel_hi:[1,0]
	v_pk_mul_f32 v[168:169], v[158:159], v[168:169]
	v_rcp_f32_e32 v220, v220
	v_rcp_f32_e32 v221, v221
	v_pk_add_f32 v[222:223], v[222:223], 0 op_sel_hi:[1,0]
	v_pk_mul_f32 v[178:179], v[160:161], v[178:179]
	v_pk_fma_f32 v[168:169], v[102:103], v[154:155], v[168:169]
	v_pk_add_f32 v[224:225], v[226:227], 0 op_sel_hi:[1,0]
	v_pk_fma_f32 v[178:179], v[104:105], v[156:157], v[178:179]
	v_pk_fma_f32 v[168:169], v[146:147], v[222:223], v[168:169]
	v_pk_fma_f32 v[178:179], v[148:149], v[224:225], v[178:179]
	v_pk_add_f32 v[168:169], v[150:151], v[168:169]
	v_pk_mul_f32 v[214:215], v[214:215], v[218:219]
	v_pk_add_f32 v[178:179], v[152:153], v[178:179]
	v_pk_mul_f32 v[168:169], v[214:215], v[168:169]
	v_pk_mul_f32 v[214:215], v[216:217], v[220:221]
	v_cvt_pk_bf16_f32 v168, v168, v169
	v_pk_mul_f32 v[178:179], v[214:215], v[178:179]
	s_nop 0
	v_cvt_pk_bf16_f32 v169, v178, v179
	v_mov_b64_e32 v[178:179], s[22:23]
	v_mad_i64_i32 v[178:179], s[48:49], v243, s72, v[178:179]
	v_lshl_add_u64 v[178:179], v[176:177], 1, v[178:179]
	global_store_dwordx2 v[178:179], v[168:169], off offset:32
.LBB0_1126:
	s_or_b64 exec, exec, s[46:47]
	v_mov_b32_dpp v168, v114 row_shr:1 row_mask:0xf bank_mask:0xf bound_ctrl:1
	v_mov_b32_dpp v169, v115 row_shr:1 row_mask:0xf bank_mask:0xf bound_ctrl:1
	v_mov_b32_dpp v218, v116 row_shr:1 row_mask:0xf bank_mask:0xf bound_ctrl:1
	v_mov_b32_dpp v219, v117 row_shr:1 row_mask:0xf bank_mask:0xf bound_ctrl:1
	v_mov_b32_dpp v178, v114 row_shr:2 row_mask:0xf bank_mask:0xf bound_ctrl:1
	v_mov_b32_dpp v179, v115 row_shr:2 row_mask:0xf bank_mask:0xf bound_ctrl:1
	v_pk_add_f32 v[212:213], v[212:213], v[218:219]
	v_pk_add_f32 v[168:169], v[208:209], v[168:169]
	v_mov_b32_dpp v220, v116 row_shr:2 row_mask:0xf bank_mask:0xf bound_ctrl:1
	v_mov_b32_dpp v221, v117 row_shr:2 row_mask:0xf bank_mask:0xf bound_ctrl:1
	v_pk_add_f32 v[178:179], v[206:207], v[178:179]
	s_waitcnt vmcnt(0)
	v_pk_mul_f32 v[168:169], v[142:143], v[168:169]
	v_pk_mul_f32 v[206:207], v[144:145], v[212:213]
	v_pk_add_f32 v[208:209], v[210:211], v[220:221]
	v_pk_fma_f32 v[206:207], v[116:117], v[140:141], v[206:207]
	v_pk_fma_f32 v[168:169], v[114:115], v[138:139], v[168:169]
	v_mov_b32_dpp v218, v88 row_shr:1 row_mask:0xf bank_mask:0xf bound_ctrl:1
	v_pk_fma_f32 v[168:169], v[134:135], v[178:179], v[168:169]
	v_pk_fma_f32 v[178:179], v[136:137], v[208:209], v[206:207]
	v_mov_b32_dpp v206, v86 row_shr:1 row_mask:0xf bank_mask:0xf bound_ctrl:1
	v_mov_b32_dpp v207, v87 row_shr:1 row_mask:0xf bank_mask:0xf bound_ctrl:1
	v_mov_b32_dpp v219, v89 row_shr:1 row_mask:0xf bank_mask:0xf bound_ctrl:1
	v_pk_add_f32 v[186:187], v[186:187], v[218:219]
	v_pk_add_f32 v[182:183], v[182:183], v[206:207]
	v_mov_b32_dpp v208, v86 row_shr:2 row_mask:0xf bank_mask:0xf bound_ctrl:1
	v_mov_b32_dpp v209, v87 row_shr:2 row_mask:0xf bank_mask:0xf bound_ctrl:1
	v_mov_b32_dpp v220, v88 row_shr:2 row_mask:0xf bank_mask:0xf bound_ctrl:1
	v_mov_b32_dpp v221, v89 row_shr:2 row_mask:0xf bank_mask:0xf bound_ctrl:1
	v_pk_mul_f32 v[182:183], v[158:159], v[182:183]
	v_pk_mul_f32 v[186:187], v[160:161], v[186:187]
	v_pk_add_f32 v[178:179], v[132:133], v[178:179]
	v_pk_add_f32 v[168:169], v[130:131], v[168:169]
	v_pk_add_f32 v[184:185], v[184:185], v[220:221]
	v_pk_add_f32 v[180:181], v[180:181], v[208:209]
	v_pk_fma_f32 v[186:187], v[88:89], v[156:157], v[186:187]
	v_pk_fma_f32 v[182:183], v[86:87], v[154:155], v[182:183]
	v_mov_b32_dpp v214, v114 row_shl:15 row_mask:0xf bank_mask:0xf bound_ctrl:1
	v_pk_fma_f32 v[180:181], v[146:147], v[180:181], v[182:183]
	v_pk_fma_f32 v[182:183], v[148:149], v[184:185], v[186:187]
	v_mul_f32_e32 v184, 0xbfb8aa3b, v168
	v_mul_f32_e32 v185, 0xbfb8aa3b, v169
	v_mul_f32_e32 v186, 0xbfb8aa3b, v178
	v_mul_f32_e32 v187, 0xbfb8aa3b, v179
	v_exp_f32_e32 v184, v184
	v_exp_f32_e32 v185, v185
	v_exp_f32_e32 v186, v186
	v_exp_f32_e32 v187, v187
	v_add_f32_e32 v184, 1.0, v184
	v_add_f32_e32 v185, 1.0, v185
	v_add_f32_e32 v186, 1.0, v186
	v_add_f32_e32 v187, 1.0, v187
	v_rcp_f32_e32 v184, v184
	v_rcp_f32_e32 v185, v185
	v_rcp_f32_e32 v186, v186
	v_rcp_f32_e32 v187, v187
	v_pk_add_f32 v[182:183], v[152:153], v[182:183]
	v_pk_add_f32 v[180:181], v[150:151], v[180:181]
	v_pk_mul_f32 v[168:169], v[168:169], v[184:185]
	v_pk_mul_f32 v[178:179], v[178:179], v[186:187]
	v_pk_mul_f32 v[168:169], v[168:169], v[180:181]
	v_pk_mul_f32 v[178:179], v[178:179], v[182:183]
	v_cvt_pk_bf16_f32 v168, v168, v169
	v_cvt_pk_bf16_f32 v169, v178, v179
	v_mov_b32_dpp v215, v115 row_shl:15 row_mask:0xf bank_mask:0xf bound_ctrl:1
	global_store_dwordx2 v[192:193], v[168:169], off offset:32
	v_mov_b32_dpp v168, v98 row_shr:1 row_mask:0xf bank_mask:0xf bound_ctrl:1
	v_mov_b32_dpp v169, v99 row_shr:1 row_mask:0xf bank_mask:0xf bound_ctrl:1
	v_mov_b32_dpp v216, v114 row_shl:14 row_mask:0xf bank_mask:0xf bound_ctrl:1
	v_mov_b32_dpp v217, v115 row_shl:14 row_mask:0xf bank_mask:0xf bound_ctrl:1
	v_mov_b32_dpp v222, v116 row_shl:15 row_mask:0xf bank_mask:0xf bound_ctrl:1
	v_mov_b32_dpp v223, v117 row_shl:15 row_mask:0xf bank_mask:0xf bound_ctrl:1
	v_mov_b32_dpp v186, v98 row_shr:2 row_mask:0xf bank_mask:0xf bound_ctrl:1
	v_mov_b32_dpp v187, v99 row_shr:2 row_mask:0xf bank_mask:0xf bound_ctrl:1
	v_mov_b32_dpp v192, v100 row_shr:1 row_mask:0xf bank_mask:0xf bound_ctrl:1
	v_mov_b32_dpp v193, v101 row_shr:1 row_mask:0xf bank_mask:0xf bound_ctrl:1
	v_pk_add_f32 v[168:169], v[214:215], v[168:169]
	v_mov_b32_dpp v210, v86 row_shl:15 row_mask:0xf bank_mask:0xf bound_ctrl:1
	v_mov_b32_dpp v211, v87 row_shl:15 row_mask:0xf bank_mask:0xf bound_ctrl:1
	v_mov_b32_dpp v226, v88 row_shl:15 row_mask:0xf bank_mask:0xf bound_ctrl:1
	v_mov_b32_dpp v227, v89 row_shl:15 row_mask:0xf bank_mask:0xf bound_ctrl:1
	v_pk_add_f32 v[192:193], v[222:223], v[192:193]
	v_pk_add_f32 v[186:187], v[216:217], v[186:187]
	v_pk_mul_f32 v[168:169], v[142:143], v[168:169]
	v_mov_b32_dpp v216, v74 row_shr:1 row_mask:0xf bank_mask:0xf bound_ctrl:1
	v_mov_b32_dpp v217, v75 row_shr:1 row_mask:0xf bank_mask:0xf bound_ctrl:1
	v_mov_b32_dpp v220, v76 row_shr:1 row_mask:0xf bank_mask:0xf bound_ctrl:1
	v_mov_b32_dpp v221, v77 row_shr:1 row_mask:0xf bank_mask:0xf bound_ctrl:1
	v_mov_b32_dpp v224, v116 row_shl:14 row_mask:0xf bank_mask:0xf bound_ctrl:1
	v_mov_b32_dpp v225, v117 row_shl:14 row_mask:0xf bank_mask:0xf bound_ctrl:1
	v_mov_b32_dpp v212, v86 row_shl:14 row_mask:0xf bank_mask:0xf bound_ctrl:1
	v_mov_b32_dpp v213, v87 row_shl:14 row_mask:0xf bank_mask:0xf bound_ctrl:1
	v_mov_b32_dpp v206, v100 row_shr:2 row_mask:0xf bank_mask:0xf bound_ctrl:1
	v_mov_b32_dpp v207, v101 row_shr:2 row_mask:0xf bank_mask:0xf bound_ctrl:1
	v_pk_mul_f32 v[192:193], v[144:145], v[192:193]
	v_pk_fma_f32 v[168:169], v[98:99], v[138:139], v[168:169]
	v_mov_b32_dpp v218, v74 row_shr:2 row_mask:0xf bank_mask:0xf bound_ctrl:1
	v_mov_b32_dpp v219, v75 row_shr:2 row_mask:0xf bank_mask:0xf bound_ctrl:1
	v_pk_add_f32 v[220:221], v[226:227], v[220:221]
	v_pk_add_f32 v[210:211], v[210:211], v[216:217]
	v_mov_b32_dpp v228, v88 row_shl:14 row_mask:0xf bank_mask:0xf bound_ctrl:1
	v_mov_b32_dpp v229, v89 row_shl:14 row_mask:0xf bank_mask:0xf bound_ctrl:1
	v_pk_add_f32 v[206:207], v[224:225], v[206:207]
	v_pk_fma_f32 v[192:193], v[100:101], v[140:141], v[192:193]
	v_pk_fma_f32 v[168:169], v[134:135], v[186:187], v[168:169]
	v_mov_b32_dpp v222, v76 row_shr:2 row_mask:0xf bank_mask:0xf bound_ctrl:1
	v_mov_b32_dpp v223, v77 row_shr:2 row_mask:0xf bank_mask:0xf bound_ctrl:1
	v_pk_add_f32 v[212:213], v[212:213], v[218:219]
	v_pk_mul_f32 v[210:211], v[158:159], v[210:211]
	v_pk_mul_f32 v[218:219], v[160:161], v[220:221]
	v_pk_fma_f32 v[186:187], v[136:137], v[206:207], v[192:193]
	v_pk_add_f32 v[168:169], v[130:131], v[168:169]
	v_pk_add_f32 v[216:217], v[228:229], v[222:223]
	v_pk_fma_f32 v[218:219], v[76:77], v[156:157], v[218:219]
	v_pk_fma_f32 v[210:211], v[74:75], v[154:155], v[210:211]
	v_pk_add_f32 v[214:215], v[132:133], v[186:187]
	v_pk_fma_f32 v[210:211], v[146:147], v[212:213], v[210:211]
	v_pk_fma_f32 v[212:213], v[148:149], v[216:217], v[218:219]
	v_mul_f32_e32 v216, 0xbfb8aa3b, v168
	v_mul_f32_e32 v217, 0xbfb8aa3b, v169
	v_exp_f32_e32 v216, v216
	v_exp_f32_e32 v217, v217
	v_mul_f32_e32 v218, 0xbfb8aa3b, v214
	v_mul_f32_e32 v219, 0xbfb8aa3b, v215
	v_exp_f32_e32 v218, v218
	v_exp_f32_e32 v219, v219
	v_add_f32_e32 v216, 1.0, v216
	v_add_f32_e32 v217, 1.0, v217
	v_rcp_f32_e32 v216, v216
	v_rcp_f32_e32 v217, v217
	v_add_f32_e32 v218, 1.0, v218
	v_add_f32_e32 v219, 1.0, v219
	v_rcp_f32_e32 v218, v218
	v_rcp_f32_e32 v219, v219
	v_pk_add_f32 v[210:211], v[150:151], v[210:211]
	v_pk_mul_f32 v[168:169], v[168:169], v[216:217]
	v_pk_add_f32 v[212:213], v[152:153], v[212:213]
	v_pk_mul_f32 v[168:169], v[168:169], v[210:211]
	v_pk_mul_f32 v[210:211], v[214:215], v[218:219]
	v_cvt_pk_bf16_f32 v168, v168, v169
	v_pk_mul_f32 v[210:211], v[210:211], v[212:213]
	v_mov_b32_dpp v180, v98 row_shl:15 row_mask:0xf bank_mask:0xf bound_ctrl:1
	v_cvt_pk_bf16_f32 v169, v210, v211
	v_mov_b32_dpp v178, v98 row_shl:14 row_mask:0xf bank_mask:0xf bound_ctrl:1
	v_mov_b32_dpp v181, v99 row_shl:15 row_mask:0xf bank_mask:0xf bound_ctrl:1
	v_mov_b32_dpp v179, v99 row_shl:14 row_mask:0xf bank_mask:0xf bound_ctrl:1
	v_mov_b32_dpp v184, v100 row_shl:15 row_mask:0xf bank_mask:0xf bound_ctrl:1
	v_mov_b32_dpp v182, v100 row_shl:14 row_mask:0xf bank_mask:0xf bound_ctrl:1
	v_mov_b32_dpp v185, v101 row_shl:15 row_mask:0xf bank_mask:0xf bound_ctrl:1
	v_mov_b32_dpp v183, v101 row_shl:14 row_mask:0xf bank_mask:0xf bound_ctrl:1
	v_mov_b32_dpp v192, v74 row_shl:15 row_mask:0xf bank_mask:0xf bound_ctrl:1
	v_mov_b32_dpp v186, v74 row_shl:14 row_mask:0xf bank_mask:0xf bound_ctrl:1
	v_mov_b32_dpp v193, v75 row_shl:15 row_mask:0xf bank_mask:0xf bound_ctrl:1
	v_mov_b32_dpp v187, v75 row_shl:14 row_mask:0xf bank_mask:0xf bound_ctrl:1
	v_mov_b32_dpp v208, v76 row_shl:15 row_mask:0xf bank_mask:0xf bound_ctrl:1
	v_mov_b32_dpp v206, v76 row_shl:14 row_mask:0xf bank_mask:0xf bound_ctrl:1
	v_mov_b32_dpp v209, v77 row_shl:15 row_mask:0xf bank_mask:0xf bound_ctrl:1
	v_mov_b32_dpp v207, v77 row_shl:14 row_mask:0xf bank_mask:0xf bound_ctrl:1
	global_store_dwordx2 v[194:195], v[168:169], off offset:32
	v_mov_b32_dpp v212, v82 row_shr:1 row_mask:0xf bank_mask:0xf bound_ctrl:1
	v_mov_b32_dpp v194, v82 row_shr:2 row_mask:0xf bank_mask:0xf bound_ctrl:1
	v_mov_b32_dpp v213, v83 row_shr:1 row_mask:0xf bank_mask:0xf bound_ctrl:1
	v_mov_b32_dpp v195, v83 row_shr:2 row_mask:0xf bank_mask:0xf bound_ctrl:1
	v_mov_b32_dpp v214, v84 row_shr:1 row_mask:0xf bank_mask:0xf bound_ctrl:1
	v_mov_b32_dpp v210, v84 row_shr:2 row_mask:0xf bank_mask:0xf bound_ctrl:1
	v_mov_b32_dpp v215, v85 row_shr:1 row_mask:0xf bank_mask:0xf bound_ctrl:1
	v_mov_b32_dpp v211, v85 row_shr:2 row_mask:0xf bank_mask:0xf bound_ctrl:1
	s_and_saveexec_b64 s[46:47], s[6:7]
	s_cbranch_execz .LBB0_1128
.LBB0_1128:
	s_or_b64 exec, exec, s[46:47]
	v_mov_b32_dpp v220, v66 row_shr:1 row_mask:0xf bank_mask:0xf bound_ctrl:1
	v_mov_b32_dpp v216, v66 row_shr:2 row_mask:0xf bank_mask:0xf bound_ctrl:1
	v_mov_b32_dpp v221, v67 row_shr:1 row_mask:0xf bank_mask:0xf bound_ctrl:1
	v_mov_b32_dpp v217, v67 row_shr:2 row_mask:0xf bank_mask:0xf bound_ctrl:1
	v_mov_b32_dpp v222, v68 row_shr:1 row_mask:0xf bank_mask:0xf bound_ctrl:1
	v_mov_b32_dpp v218, v68 row_shr:2 row_mask:0xf bank_mask:0xf bound_ctrl:1
	v_mov_b32_dpp v223, v69 row_shr:1 row_mask:0xf bank_mask:0xf bound_ctrl:1
	v_mov_b32_dpp v219, v69 row_shr:2 row_mask:0xf bank_mask:0xf bound_ctrl:1
	s_and_saveexec_b64 s[46:47], s[6:7]
	s_cbranch_execz .LBB0_1130
	v_add_co_u32_e32 v168, vcc, 0x5000, v188
	s_nop 1
	v_addc_co_u32_e32 v169, vcc, 0, v189, vcc
.LBB0_1130:
	s_or_b64 exec, exec, s[46:47]
	v_pk_add_f32 v[184:185], v[184:185], v[214:215]
	v_pk_add_f32 v[180:181], v[180:181], v[212:213]
	v_pk_mul_f32 v[184:185], v[144:145], v[184:185]
	v_pk_mul_f32 v[180:181], v[142:143], v[180:181]
	v_pk_add_f32 v[182:183], v[182:183], v[210:211]
	v_pk_add_f32 v[178:179], v[178:179], v[194:195]
	v_pk_fma_f32 v[184:185], v[84:85], v[140:141], v[184:185]
	v_pk_fma_f32 v[180:181], v[82:83], v[138:139], v[180:181]
	v_pk_add_f32 v[168:169], v[208:209], v[222:223]
	v_pk_fma_f32 v[178:179], v[134:135], v[178:179], v[180:181]
	v_pk_fma_f32 v[180:181], v[136:137], v[182:183], v[184:185]
	v_pk_add_f32 v[178:179], v[130:131], v[178:179]
	v_pk_add_f32 v[180:181], v[132:133], v[180:181]
	v_mul_f32_e32 v182, 0xbfb8aa3b, v178
	v_mul_f32_e32 v183, 0xbfb8aa3b, v179
	v_mul_f32_e32 v184, 0xbfb8aa3b, v180
	v_mul_f32_e32 v185, 0xbfb8aa3b, v181
	v_exp_f32_e32 v182, v182
	v_exp_f32_e32 v183, v183
	v_exp_f32_e32 v184, v184
	v_exp_f32_e32 v185, v185
	v_add_f32_e32 v182, 1.0, v182
	v_add_f32_e32 v183, 1.0, v183
	v_add_f32_e32 v184, 1.0, v184
	v_add_f32_e32 v185, 1.0, v185
	v_pk_add_f32 v[188:189], v[192:193], v[220:221]
	v_rcp_f32_e32 v182, v182
	v_rcp_f32_e32 v183, v183
	v_rcp_f32_e32 v184, v184
	v_rcp_f32_e32 v185, v185
	v_pk_mul_f32 v[188:189], v[158:159], v[188:189]
	v_pk_mul_f32 v[168:169], v[160:161], v[168:169]
	v_pk_add_f32 v[192:193], v[206:207], v[218:219]
	v_pk_add_f32 v[186:187], v[186:187], v[216:217]
	v_pk_fma_f32 v[168:169], v[68:69], v[156:157], v[168:169]
	v_pk_fma_f32 v[188:189], v[66:67], v[154:155], v[188:189]
	v_pk_fma_f32 v[168:169], v[148:149], v[192:193], v[168:169]
	v_pk_fma_f32 v[186:187], v[146:147], v[186:187], v[188:189]
	v_pk_add_f32 v[168:169], v[152:153], v[168:169]
	v_pk_add_f32 v[186:187], v[150:151], v[186:187]
	v_pk_mul_f32 v[178:179], v[178:179], v[182:183]
	v_pk_mul_f32 v[180:181], v[180:181], v[184:185]
	v_pk_mul_f32 v[178:179], v[178:179], v[186:187]
	v_pk_mul_f32 v[168:169], v[180:181], v[168:169]
	v_cvt_pk_bf16_f32 v178, v178, v179
	v_cvt_pk_bf16_f32 v179, v168, v169
	global_store_dwordx2 v[198:199], v[178:179], off offset:32
	v_mov_b32_dpp v206, v58 row_shr:1 row_mask:0xf bank_mask:0xf bound_ctrl:1
	v_mov_b32_dpp v198, v58 row_shr:2 row_mask:0xf bank_mask:0xf bound_ctrl:1
	v_mov_b32_dpp v188, v58 row_shl:15 row_mask:0xf bank_mask:0xf bound_ctrl:1
	v_mov_b32_dpp v186, v58 row_shl:14 row_mask:0xf bank_mask:0xf bound_ctrl:1
	v_mov_b32_dpp v207, v59 row_shr:1 row_mask:0xf bank_mask:0xf bound_ctrl:1
	v_mov_b32_dpp v199, v59 row_shr:2 row_mask:0xf bank_mask:0xf bound_ctrl:1
	v_mov_b32_dpp v189, v59 row_shl:15 row_mask:0xf bank_mask:0xf bound_ctrl:1
	v_mov_b32_dpp v187, v59 row_shl:14 row_mask:0xf bank_mask:0xf bound_ctrl:1
	v_mov_b32_dpp v210, v60 row_shr:1 row_mask:0xf bank_mask:0xf bound_ctrl:1
	v_mov_b32_dpp v208, v60 row_shr:2 row_mask:0xf bank_mask:0xf bound_ctrl:1
	v_mov_b32_dpp v194, v60 row_shl:15 row_mask:0xf bank_mask:0xf bound_ctrl:1
	v_mov_b32_dpp v192, v60 row_shl:14 row_mask:0xf bank_mask:0xf bound_ctrl:1
	v_mov_b32_dpp v211, v61 row_shr:1 row_mask:0xf bank_mask:0xf bound_ctrl:1
	v_mov_b32_dpp v209, v61 row_shr:2 row_mask:0xf bank_mask:0xf bound_ctrl:1
	v_mov_b32_dpp v195, v61 row_shl:15 row_mask:0xf bank_mask:0xf bound_ctrl:1
	v_mov_b32_dpp v193, v61 row_shl:14 row_mask:0xf bank_mask:0xf bound_ctrl:1
	s_and_saveexec_b64 s[46:47], s[4:5]
	s_cbranch_execz .LBB0_1132
.LBB0_1132:
	s_or_b64 exec, exec, s[46:47]
	v_mov_b32_dpp v214, v38 row_shr:1 row_mask:0xf bank_mask:0xf bound_ctrl:1
	v_mov_b32_dpp v212, v38 row_shr:2 row_mask:0xf bank_mask:0xf bound_ctrl:1
	v_mov_b32_dpp v180, v38 row_shl:15 row_mask:0xf bank_mask:0xf bound_ctrl:1
	v_mov_b32_dpp v178, v38 row_shl:14 row_mask:0xf bank_mask:0xf bound_ctrl:1
	v_mov_b32_dpp v215, v39 row_shr:1 row_mask:0xf bank_mask:0xf bound_ctrl:1
	v_mov_b32_dpp v213, v39 row_shr:2 row_mask:0xf bank_mask:0xf bound_ctrl:1
	v_mov_b32_dpp v181, v39 row_shl:15 row_mask:0xf bank_mask:0xf bound_ctrl:1
	v_mov_b32_dpp v179, v39 row_shl:14 row_mask:0xf bank_mask:0xf bound_ctrl:1
	v_mov_b32_dpp v218, v40 row_shr:1 row_mask:0xf bank_mask:0xf bound_ctrl:1
	v_mov_b32_dpp v216, v40 row_shr:2 row_mask:0xf bank_mask:0xf bound_ctrl:1
	v_mov_b32_dpp v184, v40 row_shl:15 row_mask:0xf bank_mask:0xf bound_ctrl:1
	v_mov_b32_dpp v182, v40 row_shl:14 row_mask:0xf bank_mask:0xf bound_ctrl:1
	v_mov_b32_dpp v219, v41 row_shr:1 row_mask:0xf bank_mask:0xf bound_ctrl:1
	v_mov_b32_dpp v217, v41 row_shr:2 row_mask:0xf bank_mask:0xf bound_ctrl:1
	v_mov_b32_dpp v185, v41 row_shl:15 row_mask:0xf bank_mask:0xf bound_ctrl:1
	v_mov_b32_dpp v183, v41 row_shl:14 row_mask:0xf bank_mask:0xf bound_ctrl:1
	s_and_saveexec_b64 s[46:47], s[4:5]
	s_cbranch_execz .LBB0_1134
	v_add_co_u32_e32 v168, vcc, 0x5000, v190
	s_nop 1
	v_addc_co_u32_e32 v169, vcc, 0, v191, vcc
.LBB0_1134:
	s_or_b64 exec, exec, s[46:47]
	s_and_saveexec_b64 s[46:47], s[8:9]
	s_cbranch_execz .LBB0_1136
	v_pk_add_f32 v[206:207], v[206:207], 0 op_sel_hi:[1,0]
	v_pk_add_f32 v[210:211], v[210:211], 0 op_sel_hi:[1,0]
	v_pk_mul_f32 v[206:207], v[142:143], v[206:207]
	v_pk_add_f32 v[198:199], v[198:199], 0 op_sel_hi:[1,0]
	v_pk_mul_f32 v[210:211], v[144:145], v[210:211]
	v_pk_fma_f32 v[206:207], v[58:59], v[138:139], v[206:207]
	v_pk_add_f32 v[208:209], v[208:209], 0 op_sel_hi:[1,0]
	v_pk_fma_f32 v[210:211], v[60:61], v[140:141], v[210:211]
	v_pk_fma_f32 v[198:199], v[134:135], v[198:199], v[206:207]
	v_pk_fma_f32 v[206:207], v[136:137], v[208:209], v[210:211]
	v_pk_add_f32 v[198:199], v[130:131], v[198:199]
	v_pk_add_f32 v[206:207], v[132:133], v[206:207]
	v_mul_f32_e32 v208, 0xbfb8aa3b, v198
	v_mul_f32_e32 v209, 0xbfb8aa3b, v199
	v_exp_f32_e32 v208, v208
	v_exp_f32_e32 v209, v209
	v_mul_f32_e32 v210, 0xbfb8aa3b, v206
	v_mul_f32_e32 v211, 0xbfb8aa3b, v207
	v_exp_f32_e32 v210, v210
	v_exp_f32_e32 v211, v211
	v_add_f32_e32 v208, 1.0, v208
	v_add_f32_e32 v209, 1.0, v209
	v_pk_add_f32 v[168:169], v[214:215], 0 op_sel_hi:[1,0]
	v_rcp_f32_e32 v208, v208
	v_rcp_f32_e32 v209, v209
	v_add_f32_e32 v210, 1.0, v210
	v_add_f32_e32 v211, 1.0, v211
	v_pk_add_f32 v[190:191], v[218:219], 0 op_sel_hi:[1,0]
	v_pk_mul_f32 v[168:169], v[158:159], v[168:169]
	v_rcp_f32_e32 v210, v210
	v_rcp_f32_e32 v211, v211
	v_pk_add_f32 v[212:213], v[212:213], 0 op_sel_hi:[1,0]
	v_pk_mul_f32 v[190:191], v[160:161], v[190:191]
	v_pk_fma_f32 v[168:169], v[38:39], v[154:155], v[168:169]
	v_pk_add_f32 v[214:215], v[216:217], 0 op_sel_hi:[1,0]
	v_pk_fma_f32 v[190:191], v[40:41], v[156:157], v[190:191]
	v_pk_fma_f32 v[168:169], v[146:147], v[212:213], v[168:169]
	v_pk_fma_f32 v[190:191], v[148:149], v[214:215], v[190:191]
	v_pk_add_f32 v[168:169], v[150:151], v[168:169]
	v_pk_mul_f32 v[198:199], v[198:199], v[208:209]
	v_pk_add_f32 v[190:191], v[152:153], v[190:191]
	v_pk_mul_f32 v[168:169], v[198:199], v[168:169]
	v_pk_mul_f32 v[198:199], v[206:207], v[210:211]
	v_cvt_pk_bf16_f32 v168, v168, v169
	v_pk_mul_f32 v[190:191], v[198:199], v[190:191]
	s_nop 0
	v_cvt_pk_bf16_f32 v169, v190, v191
	v_mov_b64_e32 v[190:191], s[22:23]
	v_mad_i64_i32 v[190:191], s[48:49], v244, s72, v[190:191]
	v_lshl_add_u64 v[190:191], v[176:177], 1, v[190:191]
	global_store_dwordx2 v[190:191], v[168:169], off offset:32
.LBB0_1136:
	s_or_b64 exec, exec, s[46:47]
	v_mov_b32_dpp v168, v50 row_shr:1 row_mask:0xf bank_mask:0xf bound_ctrl:1
	v_mov_b32_dpp v169, v51 row_shr:1 row_mask:0xf bank_mask:0xf bound_ctrl:1
	v_mov_b32_dpp v208, v52 row_shr:1 row_mask:0xf bank_mask:0xf bound_ctrl:1
	v_mov_b32_dpp v209, v53 row_shr:1 row_mask:0xf bank_mask:0xf bound_ctrl:1
	v_mov_b32_dpp v190, v50 row_shr:2 row_mask:0xf bank_mask:0xf bound_ctrl:1
	v_mov_b32_dpp v191, v51 row_shr:2 row_mask:0xf bank_mask:0xf bound_ctrl:1
	v_pk_add_f32 v[194:195], v[194:195], v[208:209]
	v_pk_add_f32 v[168:169], v[188:189], v[168:169]
	v_mov_b32_dpp v210, v52 row_shr:2 row_mask:0xf bank_mask:0xf bound_ctrl:1
	v_mov_b32_dpp v211, v53 row_shr:2 row_mask:0xf bank_mask:0xf bound_ctrl:1
	v_pk_add_f32 v[186:187], v[186:187], v[190:191]
	v_pk_mul_f32 v[168:169], v[142:143], v[168:169]
	v_pk_mul_f32 v[190:191], v[144:145], v[194:195]
	v_pk_add_f32 v[188:189], v[192:193], v[210:211]
	v_pk_fma_f32 v[190:191], v[52:53], v[140:141], v[190:191]
	v_pk_fma_f32 v[168:169], v[50:51], v[138:139], v[168:169]
	v_mov_b32_dpp v192, v24 row_shr:1 row_mask:0xf bank_mask:0xf bound_ctrl:1
	v_pk_fma_f32 v[168:169], v[134:135], v[186:187], v[168:169]
	v_pk_fma_f32 v[186:187], v[136:137], v[188:189], v[190:191]
	v_mov_b32_dpp v188, v22 row_shr:1 row_mask:0xf bank_mask:0xf bound_ctrl:1
	v_mov_b32_dpp v189, v23 row_shr:1 row_mask:0xf bank_mask:0xf bound_ctrl:1
	v_mov_b32_dpp v193, v25 row_shr:1 row_mask:0xf bank_mask:0xf bound_ctrl:1
	v_pk_add_f32 v[184:185], v[184:185], v[192:193]
	v_pk_add_f32 v[180:181], v[180:181], v[188:189]
	v_mov_b32_dpp v190, v22 row_shr:2 row_mask:0xf bank_mask:0xf bound_ctrl:1
	v_mov_b32_dpp v191, v23 row_shr:2 row_mask:0xf bank_mask:0xf bound_ctrl:1
	v_mov_b32_dpp v210, v24 row_shr:2 row_mask:0xf bank_mask:0xf bound_ctrl:1
	v_mov_b32_dpp v211, v25 row_shr:2 row_mask:0xf bank_mask:0xf bound_ctrl:1
	v_pk_mul_f32 v[180:181], v[158:159], v[180:181]
	v_pk_mul_f32 v[184:185], v[160:161], v[184:185]
	v_pk_add_f32 v[168:169], v[130:131], v[168:169]
	v_pk_add_f32 v[182:183], v[182:183], v[210:211]
	v_pk_add_f32 v[178:179], v[178:179], v[190:191]
	v_pk_fma_f32 v[184:185], v[24:25], v[156:157], v[184:185]
	v_pk_fma_f32 v[180:181], v[22:23], v[154:155], v[180:181]
	v_pk_add_f32 v[186:187], v[132:133], v[186:187]
	v_pk_fma_f32 v[178:179], v[146:147], v[178:179], v[180:181]
	v_pk_fma_f32 v[180:181], v[148:149], v[182:183], v[184:185]
	v_mul_f32_e32 v182, 0xbfb8aa3b, v168
	v_mul_f32_e32 v183, 0xbfb8aa3b, v169
	v_exp_f32_e32 v182, v182
	v_exp_f32_e32 v183, v183
	v_mul_f32_e32 v184, 0xbfb8aa3b, v186
	v_mul_f32_e32 v185, 0xbfb8aa3b, v187
	v_exp_f32_e32 v184, v184
	v_exp_f32_e32 v185, v185
	v_add_f32_e32 v182, 1.0, v182
	v_add_f32_e32 v183, 1.0, v183
	v_rcp_f32_e32 v182, v182
	v_rcp_f32_e32 v183, v183
	v_add_f32_e32 v184, 1.0, v184
	v_add_f32_e32 v185, 1.0, v185
	v_rcp_f32_e32 v184, v184
	v_rcp_f32_e32 v185, v185
	v_pk_add_f32 v[178:179], v[150:151], v[178:179]
	v_pk_mul_f32 v[168:169], v[168:169], v[182:183]
	v_pk_add_f32 v[180:181], v[152:153], v[180:181]
	v_pk_mul_f32 v[168:169], v[168:169], v[178:179]
	v_pk_mul_f32 v[178:179], v[186:187], v[184:185]
	v_cvt_pk_bf16_f32 v168, v168, v169
	v_pk_mul_f32 v[178:179], v[178:179], v[180:181]
	v_mov_b32_dpp v198, v50 row_shl:15 row_mask:0xf bank_mask:0xf bound_ctrl:1
	v_cvt_pk_bf16_f32 v169, v178, v179
	v_mov_b32_dpp v199, v51 row_shl:15 row_mask:0xf bank_mask:0xf bound_ctrl:1
	global_store_dwordx2 v[200:201], v[168:169], off offset:32
	v_mov_b32_dpp v168, v34 row_shr:1 row_mask:0xf bank_mask:0xf bound_ctrl:1
	v_mov_b32_dpp v169, v35 row_shr:1 row_mask:0xf bank_mask:0xf bound_ctrl:1
	v_mov_b32_dpp v212, v52 row_shl:15 row_mask:0xf bank_mask:0xf bound_ctrl:1
	v_mov_b32_dpp v213, v53 row_shl:15 row_mask:0xf bank_mask:0xf bound_ctrl:1
	v_mov_b32_dpp v188, v36 row_shr:1 row_mask:0xf bank_mask:0xf bound_ctrl:1
	v_mov_b32_dpp v189, v37 row_shr:1 row_mask:0xf bank_mask:0xf bound_ctrl:1
	v_pk_add_f32 v[168:169], v[198:199], v[168:169]
	v_mov_b32_dpp v206, v50 row_shl:14 row_mask:0xf bank_mask:0xf bound_ctrl:1
	v_mov_b32_dpp v207, v51 row_shl:14 row_mask:0xf bank_mask:0xf bound_ctrl:1
	v_mov_b32_dpp v194, v22 row_shl:15 row_mask:0xf bank_mask:0xf bound_ctrl:1
	v_mov_b32_dpp v195, v23 row_shl:15 row_mask:0xf bank_mask:0xf bound_ctrl:1
	v_mov_b32_dpp v186, v34 row_shr:2 row_mask:0xf bank_mask:0xf bound_ctrl:1
	v_mov_b32_dpp v187, v35 row_shr:2 row_mask:0xf bank_mask:0xf bound_ctrl:1
	v_pk_add_f32 v[188:189], v[212:213], v[188:189]
	v_pk_mul_f32 v[168:169], v[142:143], v[168:169]
	v_mov_b32_dpp v200, v10 row_shr:1 row_mask:0xf bank_mask:0xf bound_ctrl:1
	v_mov_b32_dpp v201, v11 row_shr:1 row_mask:0xf bank_mask:0xf bound_ctrl:1
	v_mov_b32_dpp v214, v52 row_shl:14 row_mask:0xf bank_mask:0xf bound_ctrl:1
	v_mov_b32_dpp v215, v53 row_shl:14 row_mask:0xf bank_mask:0xf bound_ctrl:1
	v_mov_b32_dpp v216, v24 row_shl:15 row_mask:0xf bank_mask:0xf bound_ctrl:1
	v_mov_b32_dpp v217, v25 row_shl:15 row_mask:0xf bank_mask:0xf bound_ctrl:1
	v_mov_b32_dpp v190, v36 row_shr:2 row_mask:0xf bank_mask:0xf bound_ctrl:1
	v_mov_b32_dpp v191, v37 row_shr:2 row_mask:0xf bank_mask:0xf bound_ctrl:1
	v_pk_add_f32 v[186:187], v[206:207], v[186:187]
	v_pk_mul_f32 v[188:189], v[144:145], v[188:189]
	v_pk_fma_f32 v[168:169], v[34:35], v[138:139], v[168:169]
	v_mov_b32_dpp v210, v12 row_shr:1 row_mask:0xf bank_mask:0xf bound_ctrl:1
	v_mov_b32_dpp v211, v13 row_shr:1 row_mask:0xf bank_mask:0xf bound_ctrl:1
	v_pk_add_f32 v[194:195], v[194:195], v[200:201]
	v_mov_b32_dpp v208, v22 row_shl:14 row_mask:0xf bank_mask:0xf bound_ctrl:1
	v_mov_b32_dpp v209, v23 row_shl:14 row_mask:0xf bank_mask:0xf bound_ctrl:1
	v_pk_add_f32 v[190:191], v[214:215], v[190:191]
	v_pk_fma_f32 v[188:189], v[36:37], v[140:141], v[188:189]
	v_pk_fma_f32 v[168:169], v[134:135], v[186:187], v[168:169]
	v_mov_b32_dpp v206, v10 row_shr:2 row_mask:0xf bank_mask:0xf bound_ctrl:1
	v_mov_b32_dpp v207, v11 row_shr:2 row_mask:0xf bank_mask:0xf bound_ctrl:1
	v_pk_add_f32 v[210:211], v[216:217], v[210:211]
	v_pk_mul_f32 v[194:195], v[158:159], v[194:195]
	v_mov_b32_dpp v218, v24 row_shl:14 row_mask:0xf bank_mask:0xf bound_ctrl:1
	v_mov_b32_dpp v219, v25 row_shl:14 row_mask:0xf bank_mask:0xf bound_ctrl:1
	v_pk_fma_f32 v[186:187], v[136:137], v[190:191], v[188:189]
	v_pk_add_f32 v[168:169], v[130:131], v[168:169]
	v_mov_b32_dpp v212, v12 row_shr:2 row_mask:0xf bank_mask:0xf bound_ctrl:1
	v_mov_b32_dpp v213, v13 row_shr:2 row_mask:0xf bank_mask:0xf bound_ctrl:1
	v_pk_add_f32 v[206:207], v[208:209], v[206:207]
	v_pk_mul_f32 v[208:209], v[160:161], v[210:211]
	v_pk_fma_f32 v[194:195], v[10:11], v[154:155], v[194:195]
	v_pk_add_f32 v[198:199], v[132:133], v[186:187]
	v_pk_add_f32 v[200:201], v[218:219], v[212:213]
	v_pk_fma_f32 v[208:209], v[12:13], v[156:157], v[208:209]
	v_pk_fma_f32 v[194:195], v[146:147], v[206:207], v[194:195]
	v_mul_f32_e32 v206, 0xbfb8aa3b, v168
	v_mul_f32_e32 v207, 0xbfb8aa3b, v169
	v_pk_fma_f32 v[200:201], v[148:149], v[200:201], v[208:209]
	v_exp_f32_e32 v206, v206
	v_exp_f32_e32 v207, v207
	v_mul_f32_e32 v208, 0xbfb8aa3b, v198
	v_mul_f32_e32 v209, 0xbfb8aa3b, v199
	v_exp_f32_e32 v208, v208
	v_exp_f32_e32 v209, v209
	v_add_f32_e32 v206, 1.0, v206
	v_add_f32_e32 v207, 1.0, v207
	v_rcp_f32_e32 v206, v206
	v_rcp_f32_e32 v207, v207
	v_add_f32_e32 v208, 1.0, v208
	v_add_f32_e32 v209, 1.0, v209
	v_rcp_f32_e32 v208, v208
	v_rcp_f32_e32 v209, v209
	v_pk_add_f32 v[194:195], v[150:151], v[194:195]
	v_pk_mul_f32 v[168:169], v[168:169], v[206:207]
	v_pk_add_f32 v[200:201], v[152:153], v[200:201]
	v_pk_mul_f32 v[168:169], v[168:169], v[194:195]
	v_pk_mul_f32 v[194:195], v[198:199], v[208:209]
	v_cvt_pk_bf16_f32 v168, v168, v169
	v_pk_mul_f32 v[194:195], v[194:195], v[200:201]
	v_mov_b32_dpp v180, v34 row_shl:15 row_mask:0xf bank_mask:0xf bound_ctrl:1
	v_cvt_pk_bf16_f32 v169, v194, v195
	v_mov_b32_dpp v178, v34 row_shl:14 row_mask:0xf bank_mask:0xf bound_ctrl:1
	v_mov_b32_dpp v181, v35 row_shl:15 row_mask:0xf bank_mask:0xf bound_ctrl:1
	v_mov_b32_dpp v179, v35 row_shl:14 row_mask:0xf bank_mask:0xf bound_ctrl:1
	v_mov_b32_dpp v184, v36 row_shl:15 row_mask:0xf bank_mask:0xf bound_ctrl:1
	v_mov_b32_dpp v182, v36 row_shl:14 row_mask:0xf bank_mask:0xf bound_ctrl:1
	v_mov_b32_dpp v185, v37 row_shl:15 row_mask:0xf bank_mask:0xf bound_ctrl:1
	v_mov_b32_dpp v183, v37 row_shl:14 row_mask:0xf bank_mask:0xf bound_ctrl:1
	v_mov_b32_dpp v188, v10 row_shl:15 row_mask:0xf bank_mask:0xf bound_ctrl:1
	v_mov_b32_dpp v186, v10 row_shl:14 row_mask:0xf bank_mask:0xf bound_ctrl:1
	v_mov_b32_dpp v189, v11 row_shl:15 row_mask:0xf bank_mask:0xf bound_ctrl:1
	v_mov_b32_dpp v187, v11 row_shl:14 row_mask:0xf bank_mask:0xf bound_ctrl:1
	v_mov_b32_dpp v192, v12 row_shl:15 row_mask:0xf bank_mask:0xf bound_ctrl:1
	v_mov_b32_dpp v190, v12 row_shl:14 row_mask:0xf bank_mask:0xf bound_ctrl:1
	v_mov_b32_dpp v193, v13 row_shl:15 row_mask:0xf bank_mask:0xf bound_ctrl:1
	v_mov_b32_dpp v191, v13 row_shl:14 row_mask:0xf bank_mask:0xf bound_ctrl:1
	global_store_dwordx2 v[202:203], v[168:169], off offset:32
	v_mov_b32_dpp v200, v18 row_shr:1 row_mask:0xf bank_mask:0xf bound_ctrl:1
	v_mov_b32_dpp v194, v18 row_shr:2 row_mask:0xf bank_mask:0xf bound_ctrl:1
	v_mov_b32_dpp v201, v19 row_shr:1 row_mask:0xf bank_mask:0xf bound_ctrl:1
	v_mov_b32_dpp v195, v19 row_shr:2 row_mask:0xf bank_mask:0xf bound_ctrl:1
	v_mov_b32_dpp v202, v20 row_shr:1 row_mask:0xf bank_mask:0xf bound_ctrl:1
	v_mov_b32_dpp v198, v20 row_shr:2 row_mask:0xf bank_mask:0xf bound_ctrl:1
	v_mov_b32_dpp v203, v21 row_shr:1 row_mask:0xf bank_mask:0xf bound_ctrl:1
	v_mov_b32_dpp v199, v21 row_shr:2 row_mask:0xf bank_mask:0xf bound_ctrl:1
	s_and_saveexec_b64 s[46:47], s[6:7]
	s_cbranch_execz .LBB0_1138
.LBB0_1138:
	s_or_b64 exec, exec, s[46:47]
	v_mov_b32_dpp v210, v2 row_shr:1 row_mask:0xf bank_mask:0xf bound_ctrl:1
	v_mov_b32_dpp v206, v2 row_shr:2 row_mask:0xf bank_mask:0xf bound_ctrl:1
	v_mov_b32_dpp v211, v3 row_shr:1 row_mask:0xf bank_mask:0xf bound_ctrl:1
	v_mov_b32_dpp v207, v3 row_shr:2 row_mask:0xf bank_mask:0xf bound_ctrl:1
	v_mov_b32_dpp v212, v4 row_shr:1 row_mask:0xf bank_mask:0xf bound_ctrl:1
	v_mov_b32_dpp v208, v4 row_shr:2 row_mask:0xf bank_mask:0xf bound_ctrl:1
	v_mov_b32_dpp v213, v5 row_shr:1 row_mask:0xf bank_mask:0xf bound_ctrl:1
	v_mov_b32_dpp v209, v5 row_shr:2 row_mask:0xf bank_mask:0xf bound_ctrl:1
	s_and_saveexec_b64 s[46:47], s[6:7]
	s_cbranch_execz .LBB0_1140
	v_add_co_u32_e32 v168, vcc, 0x5000, v196
	s_nop 1
	v_addc_co_u32_e32 v169, vcc, 0, v197, vcc
.LBB0_1140:
	s_or_b64 exec, exec, s[46:47]
	v_pk_add_f32 v[168:169], v[192:193], v[212:213]
	v_pk_add_f32 v[188:189], v[188:189], v[210:211]
	v_pk_mul_f32 v[160:161], v[160:161], v[168:169]
	v_pk_mul_f32 v[158:159], v[158:159], v[188:189]
	v_pk_add_f32 v[190:191], v[190:191], v[208:209]
	v_pk_add_f32 v[186:187], v[186:187], v[206:207]
	v_pk_fma_f32 v[156:157], v[4:5], v[156:157], v[160:161]
	v_pk_fma_f32 v[154:155], v[2:3], v[154:155], v[158:159]
	v_pk_fma_f32 v[148:149], v[148:149], v[190:191], v[156:157]
	v_pk_fma_f32 v[146:147], v[146:147], v[186:187], v[154:155]
	v_pk_add_f32 v[148:149], v[152:153], v[148:149]
	v_pk_add_f32 v[146:147], v[150:151], v[146:147]
	v_pk_add_f32 v[150:151], v[184:185], v[202:203]
	v_pk_add_f32 v[152:153], v[180:181], v[200:201]
	v_pk_mul_f32 v[144:145], v[144:145], v[150:151]
	v_pk_mul_f32 v[142:143], v[142:143], v[152:153]
	v_pk_add_f32 v[154:155], v[182:183], v[198:199]
	v_pk_add_f32 v[156:157], v[178:179], v[194:195]
	v_pk_fma_f32 v[140:141], v[20:21], v[140:141], v[144:145]
	v_pk_fma_f32 v[138:139], v[18:19], v[138:139], v[142:143]
	v_pk_fma_f32 v[136:137], v[136:137], v[154:155], v[140:141]
	v_pk_fma_f32 v[134:135], v[134:135], v[156:157], v[138:139]
	v_pk_add_f32 v[132:133], v[132:133], v[136:137]
	v_pk_add_f32 v[130:131], v[130:131], v[134:135]
	v_mul_f32_e32 v136, 0xbfb8aa3b, v132
	v_mul_f32_e32 v134, 0xbfb8aa3b, v130
	v_mul_f32_e32 v135, 0xbfb8aa3b, v131
	v_mul_f32_e32 v137, 0xbfb8aa3b, v133
	v_exp_f32_e32 v134, v134
	v_exp_f32_e32 v135, v135
	v_exp_f32_e32 v136, v136
	v_exp_f32_e32 v137, v137
	v_add_f32_e32 v134, 1.0, v134
	v_add_f32_e32 v135, 1.0, v135
	v_add_f32_e32 v136, 1.0, v136
	v_add_f32_e32 v137, 1.0, v137
	v_rcp_f32_e32 v134, v134
	v_rcp_f32_e32 v135, v135
	v_rcp_f32_e32 v136, v136
	v_rcp_f32_e32 v137, v137
	s_mov_b64 s[46:47], 0
	v_pk_mul_f32 v[130:131], v[130:131], v[134:135]
	v_pk_mul_f32 v[132:133], v[132:133], v[136:137]
	v_pk_mul_f32 v[130:131], v[130:131], v[146:147]
	v_pk_mul_f32 v[132:133], v[132:133], v[148:149]
	v_cvt_pk_bf16_f32 v130, v130, v131
	v_cvt_pk_bf16_f32 v131, v132, v133
	global_store_dwordx2 v[204:205], v[130:131], off offset:32
	s_lshl_b32 s39, s20, 2
	s_add_i32 s39, s39, s55
	s_lshl_b32 s39, s39, 1
	v_and_b32_e32 v146, 1, v1
	v_add_u32_e32 v146, s39, v146
	v_mov_b64_e32 v[148:149], s[24:25]
	v_mad_i64_i32 v[148:149], s[48:49], v146, s71, v[148:149]
	v_lshl_add_u64 v[148:149], v[176:177], 2, v[148:149]
	v_bfe_u32 v147, v1, 1, 1
	v_lshlrev_b32_e32 v147, 6, v147
	v_bfe_u32 v150, v1, 2, 1
	v_mul_u32_u24_e32 v150, 0x5800, v150
	v_add_u32_e32 v147, v147, v150
	v_bfe_u32 v150, v1, 3, 1
	v_mul_u32_u24_e32 v150, 22, v150
	v_lshlrev_b32_e32 v150, 20, v150
	v_add_u32_e32 v150, v147, v150
	v_mov_b32_e32 v151, 0
	v_lshl_add_u64 v[148:149], v[150:151], 0, v[148:149]
	s_mov_b64 s[48:49], 0x2c000
	v_lshl_add_u64 v[152:153], v[148:149], 0, s[48:49]
	v_mov_b32_e32 v130, v126
	v_mov_b32_e32 v131, v127
	v_mov_b32_e32 v132, v128
	v_mov_b32_e32 v133, v129
	v_mov_b32_e32 v134, v62
	v_mov_b32_e32 v135, v63
	v_mov_b32_e32 v136, v64
	v_mov_b32_e32 v137, v65
	v_mov_b32_dpp v130, v122 row_shr:2 row_mask:0xf bank_mask:0x1
	v_mov_b32_dpp v131, v123 row_shr:2 row_mask:0xf bank_mask:0x1
	v_mov_b32_dpp v132, v124 row_shr:2 row_mask:0xf bank_mask:0x1
	v_mov_b32_dpp v133, v125 row_shr:2 row_mask:0xf bank_mask:0x1
	v_mov_b32_dpp v134, v58 row_shr:2 row_mask:0xf bank_mask:0x1
	v_mov_b32_dpp v135, v59 row_shr:2 row_mask:0xf bank_mask:0x1
	v_mov_b32_dpp v136, v60 row_shr:2 row_mask:0xf bank_mask:0x1
	v_mov_b32_dpp v137, v61 row_shr:2 row_mask:0xf bank_mask:0x1
	v_mov_b32_dpp v130, v110 row_shr:4 row_mask:0xf bank_mask:0x2
	v_mov_b32_dpp v131, v111 row_shr:4 row_mask:0xf bank_mask:0x2
	v_mov_b32_dpp v132, v112 row_shr:4 row_mask:0xf bank_mask:0x2
	v_mov_b32_dpp v133, v113 row_shr:4 row_mask:0xf bank_mask:0x2
	v_mov_b32_dpp v134, v46 row_shr:4 row_mask:0xf bank_mask:0x2
	v_mov_b32_dpp v135, v47 row_shr:4 row_mask:0xf bank_mask:0x2
	v_mov_b32_dpp v136, v48 row_shr:4 row_mask:0xf bank_mask:0x2
	v_mov_b32_dpp v137, v49 row_shr:4 row_mask:0xf bank_mask:0x2
	v_mov_b32_dpp v130, v102 row_shr:6 row_mask:0xf bank_mask:0x2
	v_mov_b32_dpp v131, v103 row_shr:6 row_mask:0xf bank_mask:0x2
	v_mov_b32_dpp v132, v104 row_shr:6 row_mask:0xf bank_mask:0x2
	v_mov_b32_dpp v133, v105 row_shr:6 row_mask:0xf bank_mask:0x2
	v_mov_b32_dpp v134, v38 row_shr:6 row_mask:0xf bank_mask:0x2
	v_mov_b32_dpp v135, v39 row_shr:6 row_mask:0xf bank_mask:0x2
	v_mov_b32_dpp v136, v40 row_shr:6 row_mask:0xf bank_mask:0x2
	v_mov_b32_dpp v137, v41 row_shr:6 row_mask:0xf bank_mask:0x2
	v_mov_b32_dpp v130, v66 quad_perm:[0,1,2,3] row_mask:0xf bank_mask:0x8
	v_mov_b32_dpp v131, v67 quad_perm:[0,1,2,3] row_mask:0xf bank_mask:0x8
	v_mov_b32_dpp v132, v68 quad_perm:[0,1,2,3] row_mask:0xf bank_mask:0x8
	v_mov_b32_dpp v133, v69 quad_perm:[0,1,2,3] row_mask:0xf bank_mask:0x8
	v_mov_b32_dpp v134, v2 quad_perm:[0,1,2,3] row_mask:0xf bank_mask:0x8
	v_mov_b32_dpp v135, v3 quad_perm:[0,1,2,3] row_mask:0xf bank_mask:0x8
	v_mov_b32_dpp v136, v4 quad_perm:[0,1,2,3] row_mask:0xf bank_mask:0x8
	v_mov_b32_dpp v137, v5 quad_perm:[0,1,2,3] row_mask:0xf bank_mask:0x8
	v_mov_b32_dpp v130, v70 row_shl:2 row_mask:0xf bank_mask:0x8
	v_mov_b32_dpp v131, v71 row_shl:2 row_mask:0xf bank_mask:0x8
	v_mov_b32_dpp v132, v72 row_shl:2 row_mask:0xf bank_mask:0x8
	v_mov_b32_dpp v133, v73 row_shl:2 row_mask:0xf bank_mask:0x8
	v_mov_b32_dpp v134, v6 row_shl:2 row_mask:0xf bank_mask:0x8
	v_mov_b32_dpp v135, v7 row_shl:2 row_mask:0xf bank_mask:0x8
	v_mov_b32_dpp v136, v8 row_shl:2 row_mask:0xf bank_mask:0x8
	v_mov_b32_dpp v137, v9 row_shl:2 row_mask:0xf bank_mask:0x8
	v_mov_b32_dpp v130, v82 row_shl:4 row_mask:0xf bank_mask:0x4
	v_mov_b32_dpp v131, v83 row_shl:4 row_mask:0xf bank_mask:0x4
	v_mov_b32_dpp v132, v84 row_shl:4 row_mask:0xf bank_mask:0x4
	v_mov_b32_dpp v133, v85 row_shl:4 row_mask:0xf bank_mask:0x4
	v_mov_b32_dpp v134, v18 row_shl:4 row_mask:0xf bank_mask:0x4
	v_mov_b32_dpp v135, v19 row_shl:4 row_mask:0xf bank_mask:0x4
	v_mov_b32_dpp v136, v20 row_shl:4 row_mask:0xf bank_mask:0x4
	v_mov_b32_dpp v137, v21 row_shl:4 row_mask:0xf bank_mask:0x4
	v_mov_b32_dpp v130, v90 row_shl:6 row_mask:0xf bank_mask:0x4
	v_mov_b32_dpp v131, v91 row_shl:6 row_mask:0xf bank_mask:0x4
	v_mov_b32_dpp v132, v92 row_shl:6 row_mask:0xf bank_mask:0x4
	v_mov_b32_dpp v133, v93 row_shl:6 row_mask:0xf bank_mask:0x4
	v_mov_b32_dpp v134, v26 row_shl:6 row_mask:0xf bank_mask:0x4
	v_mov_b32_dpp v135, v27 row_shl:6 row_mask:0xf bank_mask:0x4
	v_mov_b32_dpp v136, v28 row_shl:6 row_mask:0xf bank_mask:0x4
	v_mov_b32_dpp v137, v29 row_shl:6 row_mask:0xf bank_mask:0x4
	global_store_dwordx4 v[148:149], v[130:133], off
	global_store_dwordx4 v[152:153], v[134:137], off
